# attention loops: per-MFMA s_setprio flips deleted (timing-only), on top of v1
# baseline (speedup 1.0000x reference)
; #define WAIT_BAR(N) asm volatile("s_waitcnt vmcnt(" #N ") lgkmcnt(0)\n\ts_barrier":::"memory")
;   #define RESC() do{ if(resc){ asm volatile("s_waitcnt lgkmcnt(0)":::"memory"); \
;       _Pragma("unroll") for(int d_=0;d_<2;++d_) _Pragma("unroll") for(int r=0;r<16;++r)o[d_][r]*=wsf[crow(r,hi)]; } }while(0)
;   #define ROT() do{sl_prev=sl_cur;sl_cur=sl_next;sl_next=(sl_next==(NSLOT-1)*SLOTB)?0:sl_next+SLOTB;}while(0)
; template<int THRL> __device__ __forceinline__ void attn_unit(int S,int b,int h,int qb,const bf16*Q,const bf16*__restrict__ K,const bf16*__restrict__ V,bf16*O,char*shm,const float mref){
;     ...
;   int t=1;
;     ...
;   for(;t+5<NT;t+=2){
;     STEP(pB0,pB1,pA0,pA1,t,true,true,true);     WAIT_BAR(2); RESC(); ROT();
.LBB0_167:
	s_mov_b32 s1, s54
	v_mov_b64_e32 v[190:191], v[82:83]
	s_mov_b32 s55, s37
	v_mov_b64_e32 v[192:193], v[84:85]
	s_mov_b32 s23, s53
	v_add_u32_e32 v182, s36, v212
	ds_read_b64_tr_b16 v[184:185], v182 offset:24576
	ds_read_b64_tr_b16 v[186:187], v182 offset:25088
	v_add_f32_e32 v82, v66, v67
	s_waitcnt lgkmcnt(9)
	v_mfma_f32_32x32x16_bf16 v[98:113], v[174:177], v[134:137], v[34:49]
	v_add_f32_e32 v82, v68, v82
	v_add_f32_e32 v82, v69, v82
	v_add_f32_e32 v82, v70, v82
	v_add_f32_e32 v122, v71, v82
	v_cvt_pk_bf16_f32 v142, v66, v67
	v_cvt_pk_bf16_f32 v143, v68, v69
	ds_read_b64_tr_b16 v[66:67], v182 offset:28672
	ds_read_b64_tr_b16 v[68:69], v182 offset:29184
	s_waitcnt lgkmcnt(10)
	v_mfma_f32_32x32x16_bf16 v[82:97], v[170:173], v[134:137], v[34:49]
	v_add_f32_e32 v122, v72, v122
	v_add_f32_e32 v122, v73, v122
	v_add_f32_e32 v122, v74, v122
	v_add_f32_e32 v122, v75, v122
	v_cvt_pk_bf16_f32 v144, v70, v71
	v_cvt_pk_bf16_f32 v145, v72, v73
	ds_read_b64_tr_b16 v[70:71], v182 offset:25600
	ds_read_b64_tr_b16 v[72:73], v182 offset:26112
	s_waitcnt lgkmcnt(11)
	v_mfma_f32_32x32x16_bf16 v[98:113], v[166:169], v[126:129], v[98:113]
	v_add_f32_e32 v122, v76, v122
	v_add_f32_e32 v122, v77, v122
	v_add_f32_e32 v122, v78, v122
	v_add_f32_e32 v122, v79, v122
	v_cvt_pk_bf16_f32 v138, v74, v75
	v_cvt_pk_bf16_f32 v139, v76, v77
	ds_read_b64_tr_b16 v[74:75], v182 offset:29696
	ds_read_b64_tr_b16 v[76:77], v182 offset:30208
	s_waitcnt lgkmcnt(12)
	v_mfma_f32_32x32x16_bf16 v[82:97], v[162:165], v[126:129], v[82:97]
	v_add_f32_e32 v122, v80, v122
	v_add_f32_e32 v122, v81, v122
	v_add_f32_e32 v122, v50, v122
	v_add_f32_e32 v122, v51, v122
	v_cvt_pk_bf16_f32 v140, v78, v79
	v_cvt_pk_bf16_f32 v141, v80, v81
	ds_read_b64_tr_b16 v[78:79], v182 offset:26624
	ds_read_b64_tr_b16 v[80:81], v182 offset:27136
	s_waitcnt lgkmcnt(13)
	v_mfma_f32_32x32x16_bf16 v[98:113], v[158:161], v[118:121], v[98:113]
	v_add_f32_e32 v122, v52, v122
	v_add_f32_e32 v122, v53, v122
	v_add_f32_e32 v122, v54, v122
	v_add_f32_e32 v122, v55, v122
	v_cvt_pk_bf16_f32 v130, v50, v51
	v_cvt_pk_bf16_f32 v131, v52, v53
	ds_read_b64_tr_b16 v[50:51], v182 offset:30720
	ds_read_b64_tr_b16 v[52:53], v182 offset:31232
	s_waitcnt lgkmcnt(14)
	v_mfma_f32_32x32x16_bf16 v[82:97], v[154:157], v[118:121], v[82:97]
	v_add_f32_e32 v122, v56, v122
	v_add_f32_e32 v122, v57, v122
	v_add_f32_e32 v122, v58, v122
	v_add_f32_e32 v122, v59, v122
	v_cvt_pk_bf16_f32 v132, v54, v55
	v_cvt_pk_bf16_f32 v133, v56, v57
	ds_read_b64_tr_b16 v[54:55], v182 offset:27648
	ds_read_b64_tr_b16 v[56:57], v182 offset:28160
	s_waitcnt lgkmcnt(14)
	v_mfma_f32_32x32x16_bf16 v[98:113], v[150:153], v[114:117], v[98:113]
	v_add_f32_e32 v122, v60, v122
	v_add_f32_e32 v122, v61, v122
	v_add_f32_e32 v122, v62, v122
	v_add_f32_e32 v150, v63, v122
	v_cvt_pk_bf16_f32 v122, v58, v59
	v_cvt_pk_bf16_f32 v123, v60, v61
	ds_read_b64_tr_b16 v[58:59], v182 offset:31744
	ds_read_b64_tr_b16 v[60:61], v182 offset:32256
	v_mfma_f32_32x32x16_bf16 v[82:97], v[146:149], v[114:117], v[82:97]
	v_add_f32_e32 v124, v64, v150
	v_add_f32_e32 v124, v65, v124
	v_add_f32_e32 v182, 0, v124
	v_cvt_pk_bf16_f32 v124, v62, v63
	v_cvt_pk_bf16_f32 v125, v64, v65
	v_lshl_add_u64 v[62:63], v[180:181], 0, s[74:75]
	s_add_i32 s30, s53, s51
	s_mov_b32 s31, m0
	s_mov_b32 m0, s30
	s_nop 0
	global_load_lds_dwordx4 v[62:63], off
	s_mov_b32 m0, s31
	v_lshl_add_u64 v[62:63], v[178:179], 0, s[74:75]
	s_add_i32 s30, s54, s52
	s_mov_b32 s31, m0
	s_mov_b32 m0, s30
	s_nop 0
	global_load_lds_dwordx4 v[62:63], off
	s_mov_b32 m0, s31
	s_waitcnt lgkmcnt(14)
	v_mfma_f32_32x32x16_bf16 v[2:17], v[142:145], v[184:187], v[2:17]
	v_exp_f32_e32 v98, v98
	v_exp_f32_e32 v99, v99
	v_exp_f32_e32 v100, v100
	v_exp_f32_e32 v101, v101
	s_waitcnt lgkmcnt(12)
	v_mfma_f32_32x32x16_bf16 v[18:33], v[142:145], v[66:69], v[18:33]
	v_exp_f32_e32 v102, v102
	v_exp_f32_e32 v103, v103
	v_exp_f32_e32 v104, v104
	v_exp_f32_e32 v105, v105
	v_add_u32_e32 v66, s1, v213
	ds_read_b128 v[62:65], v66
	ds_read_b128 v[146:149], v66 offset:512
	s_waitcnt lgkmcnt(12)
	v_mfma_f32_32x32x16_bf16 v[2:17], v[138:141], v[70:73], v[2:17]
	v_exp_f32_e32 v106, v106
	v_exp_f32_e32 v107, v107
	v_exp_f32_e32 v108, v108
	v_exp_f32_e32 v109, v109
	ds_read_b128 v[150:153], v66 offset:2048
	ds_read_b128 v[154:157], v66 offset:2560
	s_waitcnt lgkmcnt(12)
	v_mfma_f32_32x32x16_bf16 v[18:33], v[138:141], v[74:77], v[18:33]
	v_exp_f32_e32 v110, v110
	v_exp_f32_e32 v111, v111
	v_exp_f32_e32 v112, v112
	v_exp_f32_e32 v113, v113
	ds_read_b128 v[158:161], v66 offset:4096
	ds_read_b128 v[162:165], v66 offset:4608
	s_waitcnt lgkmcnt(12)
	v_mfma_f32_32x32x16_bf16 v[2:17], v[130:133], v[78:81], v[2:17]
	v_exp_f32_e32 v82, v82
	v_exp_f32_e32 v83, v83
	v_exp_f32_e32 v84, v84
	v_exp_f32_e32 v85, v85
	ds_read_b128 v[166:169], v66 offset:6144
	ds_read_b128 v[170:173], v66 offset:6656
	s_waitcnt lgkmcnt(12)
	v_mfma_f32_32x32x16_bf16 v[18:33], v[130:133], v[50:53], v[18:33]
	v_exp_f32_e32 v86, v86
	v_exp_f32_e32 v87, v87
	v_exp_f32_e32 v88, v88
	v_exp_f32_e32 v89, v89
	s_waitcnt lgkmcnt(10)
	v_mfma_f32_32x32x16_bf16 v[2:17], v[122:125], v[54:57], v[2:17]
	v_exp_f32_e32 v90, v90
	v_exp_f32_e32 v91, v91
	v_exp_f32_e32 v92, v92
	v_exp_f32_e32 v93, v93
	s_waitcnt lgkmcnt(8)
	v_mfma_f32_32x32x16_bf16 v[18:33], v[122:125], v[58:61], v[18:33]
	v_exp_f32_e32 v94, v94
	v_exp_f32_e32 v95, v95
	v_exp_f32_e32 v96, v96
	v_exp_f32_e32 v97, v97
	s_waitcnt vmcnt(2) lgkmcnt(0)
	s_barrier
; #define WAIT_BAR(N) asm volatile("s_waitcnt vmcnt(" #N ") lgkmcnt(0)\n\ts_barrier":::"memory")
;   #define RESC() do{ if(resc){ asm volatile("s_waitcnt lgkmcnt(0)":::"memory"); \
;       _Pragma("unroll") for(int d_=0;d_<2;++d_) _Pragma("unroll") for(int r=0;r<16;++r)o[d_][r]*=wsf[crow(r,hi)]; } }while(0)
;   #define ROT() do{sl_prev=sl_cur;sl_cur=sl_next;sl_next=(sl_next==(NSLOT-1)*SLOTB)?0:sl_next+SLOTB;}while(0)
; template<int THRL> __device__ __forceinline__ void attn_unit(int S,int b,int h,int qb,const bf16*Q,const bf16*__restrict__ K,const bf16*__restrict__ V,bf16*O,char*shm,const float mref){
;     ...
;   int t=1;
;     ...
;   for(;t+5<NT;t+=2){
;     STEP(pB0,pB1,pA0,pA1,t,true,true,true);     WAIT_BAR(2); RESC(); ROT();
;     STEP(pA0,pA1,pB0,pB1,t+1,true,true,true);   WAIT_BAR(2); RESC(); ROT();
	s_add_i32 s30, s54, 0x2000
	s_cmpk_lg_i32 s54, 0x4000
	s_cselect_b32 s53, s30, 0
	v_add_u32_e32 v183, s23, v212
	ds_read_b64_tr_b16 v[174:175], v183 offset:24576
	ds_read_b64_tr_b16 v[176:177], v183 offset:25088
	v_add_f32_e32 v50, v98, v99
	s_waitcnt lgkmcnt(9)
	v_mfma_f32_32x32x16_bf16 v[66:81], v[62:65], v[134:137], v[34:49]
	v_add_f32_e32 v50, v100, v50
	v_add_f32_e32 v50, v101, v50
	v_add_f32_e32 v50, v102, v50
	v_add_f32_e32 v122, v103, v50
	v_cvt_pk_bf16_f32 v142, v98, v99
	v_cvt_pk_bf16_f32 v143, v100, v101
	ds_read_b64_tr_b16 v[98:99], v183 offset:28672
	ds_read_b64_tr_b16 v[100:101], v183 offset:29184
	s_waitcnt lgkmcnt(10)
	v_mfma_f32_32x32x16_bf16 v[50:65], v[146:149], v[134:137], v[34:49]
	v_add_f32_e32 v122, v104, v122
	v_add_f32_e32 v122, v105, v122
	v_add_f32_e32 v122, v106, v122
	v_add_f32_e32 v122, v107, v122
	v_cvt_pk_bf16_f32 v144, v102, v103
	v_cvt_pk_bf16_f32 v145, v104, v105
	ds_read_b64_tr_b16 v[102:103], v183 offset:25600
	ds_read_b64_tr_b16 v[104:105], v183 offset:26112
	s_waitcnt lgkmcnt(11)
	v_mfma_f32_32x32x16_bf16 v[66:81], v[150:153], v[126:129], v[66:81]
	v_add_f32_e32 v122, v108, v122
	v_add_f32_e32 v122, v109, v122
	v_add_f32_e32 v122, v110, v122
	v_add_f32_e32 v122, v111, v122
	v_cvt_pk_bf16_f32 v138, v106, v107
	v_cvt_pk_bf16_f32 v139, v108, v109
	ds_read_b64_tr_b16 v[106:107], v183 offset:29696
	ds_read_b64_tr_b16 v[108:109], v183 offset:30208
	s_waitcnt lgkmcnt(12)
	v_mfma_f32_32x32x16_bf16 v[50:65], v[154:157], v[126:129], v[50:65]
	v_add_f32_e32 v122, v112, v122
	v_add_f32_e32 v122, v113, v122
	v_add_f32_e32 v122, v82, v122
	v_add_f32_e32 v122, v83, v122
	v_cvt_pk_bf16_f32 v140, v110, v111
	v_cvt_pk_bf16_f32 v141, v112, v113
	ds_read_b64_tr_b16 v[110:111], v183 offset:26624
	ds_read_b64_tr_b16 v[112:113], v183 offset:27136
	s_waitcnt lgkmcnt(13)
	v_mfma_f32_32x32x16_bf16 v[66:81], v[158:161], v[118:121], v[66:81]
	v_add_f32_e32 v122, v84, v122
	v_add_f32_e32 v122, v85, v122
	v_add_f32_e32 v122, v86, v122
	v_add_f32_e32 v122, v87, v122
	v_cvt_pk_bf16_f32 v130, v82, v83
	v_cvt_pk_bf16_f32 v131, v84, v85
	ds_read_b64_tr_b16 v[82:83], v183 offset:30720
	ds_read_b64_tr_b16 v[84:85], v183 offset:31232
	s_waitcnt lgkmcnt(14)
	v_mfma_f32_32x32x16_bf16 v[50:65], v[162:165], v[118:121], v[50:65]
	v_add_f32_e32 v122, v88, v122
	v_add_f32_e32 v122, v89, v122
	v_add_f32_e32 v122, v90, v122
	v_add_f32_e32 v122, v91, v122
	v_cvt_pk_bf16_f32 v132, v86, v87
	v_cvt_pk_bf16_f32 v133, v88, v89
	ds_read_b64_tr_b16 v[86:87], v183 offset:27648
	ds_read_b64_tr_b16 v[88:89], v183 offset:28160
	s_waitcnt lgkmcnt(14)
	v_mfma_f32_32x32x16_bf16 v[66:81], v[166:169], v[114:117], v[66:81]
	v_add_f32_e32 v122, v92, v122
	v_add_f32_e32 v122, v93, v122
	v_add_f32_e32 v122, v94, v122
	v_add_f32_e32 v146, v95, v122
	v_cvt_pk_bf16_f32 v122, v90, v91
	v_cvt_pk_bf16_f32 v123, v92, v93
	ds_read_b64_tr_b16 v[90:91], v183 offset:31744
	ds_read_b64_tr_b16 v[92:93], v183 offset:32256
	v_mfma_f32_32x32x16_bf16 v[50:65], v[170:173], v[114:117], v[50:65]
	v_add_f32_e32 v124, v96, v146
	v_add_f32_e32 v124, v97, v124
	v_add_f32_e32 v183, 0, v124
	v_cvt_pk_bf16_f32 v124, v94, v95
	v_cvt_pk_bf16_f32 v125, v96, v97
	s_add_i32 s23, s54, s51
	s_mov_b32 s30, m0
	s_mov_b32 m0, s23
	s_nop 0
	global_load_lds_dwordx4 v[180:181], off
	s_mov_b32 m0, s30
	s_add_i32 s23, s53, s52
	s_mov_b32 s30, m0
	s_mov_b32 m0, s23
	s_nop 0
	global_load_lds_dwordx4 v[178:179], off
	s_mov_b32 m0, s30
	s_waitcnt lgkmcnt(14)
	v_mfma_f32_32x32x16_bf16 v[2:17], v[142:145], v[174:177], v[2:17]
	v_exp_f32_e32 v66, v66
	v_exp_f32_e32 v67, v67
	v_exp_f32_e32 v68, v68
	v_exp_f32_e32 v69, v69
	s_waitcnt lgkmcnt(12)
	v_mfma_f32_32x32x16_bf16 v[18:33], v[142:145], v[98:101], v[18:33]
	v_exp_f32_e32 v70, v70
	v_exp_f32_e32 v71, v71
	v_exp_f32_e32 v72, v72
	v_exp_f32_e32 v73, v73
	v_add_u32_e32 v94, s53, v213
	ds_read_b128 v[174:177], v94
	ds_read_b128 v[170:173], v94 offset:512
	s_waitcnt lgkmcnt(12)
	v_mfma_f32_32x32x16_bf16 v[2:17], v[138:141], v[102:105], v[2:17]
	v_exp_f32_e32 v74, v74
	v_exp_f32_e32 v75, v75
	v_exp_f32_e32 v76, v76
	v_exp_f32_e32 v77, v77
	ds_read_b128 v[166:169], v94 offset:2048
	ds_read_b128 v[162:165], v94 offset:2560
	s_waitcnt lgkmcnt(12)
	v_mfma_f32_32x32x16_bf16 v[18:33], v[138:141], v[106:109], v[18:33]
	v_exp_f32_e32 v78, v78
	v_exp_f32_e32 v79, v79
	v_exp_f32_e32 v80, v80
	v_exp_f32_e32 v81, v81
	ds_read_b128 v[158:161], v94 offset:4096
	ds_read_b128 v[154:157], v94 offset:4608
	s_waitcnt lgkmcnt(12)
	v_mfma_f32_32x32x16_bf16 v[2:17], v[130:133], v[110:113], v[2:17]
	v_exp_f32_e32 v50, v50
	v_exp_f32_e32 v51, v51
	v_exp_f32_e32 v52, v52
	v_exp_f32_e32 v53, v53
	ds_read_b128 v[150:153], v94 offset:6144
	ds_read_b128 v[146:149], v94 offset:6656
	s_waitcnt lgkmcnt(12)
	v_mfma_f32_32x32x16_bf16 v[18:33], v[130:133], v[82:85], v[18:33]
	v_exp_f32_e32 v54, v54
	v_exp_f32_e32 v55, v55
	v_exp_f32_e32 v56, v56
	v_exp_f32_e32 v57, v57
	s_waitcnt lgkmcnt(10)
	v_mfma_f32_32x32x16_bf16 v[2:17], v[122:125], v[86:89], v[2:17]
	v_exp_f32_e32 v58, v58
	v_exp_f32_e32 v59, v59
	v_exp_f32_e32 v60, v60
	v_exp_f32_e32 v61, v61
	s_waitcnt lgkmcnt(8)
	v_mfma_f32_32x32x16_bf16 v[18:33], v[122:125], v[90:93], v[18:33]
	v_exp_f32_e32 v62, v62
	v_exp_f32_e32 v63, v63
	v_exp_f32_e32 v64, v64
	v_exp_f32_e32 v65, v65
	s_add_i32 s23, s53, 0x2000
	s_waitcnt vmcnt(2) lgkmcnt(0)
	s_barrier
	s_cmpk_lg_i32 s53, 0x4000
	v_add_f32_e32 v82, v201, v182
	s_cselect_b32 s54, s23, 0
	s_add_i32 s0, s0, 2
	s_add_i32 s37, s37, 2
	v_add_f32_e32 v201, v82, v183
	v_lshl_add_u64 v[178:179], v[178:179], 0, s[28:29]
	v_lshl_add_u64 v[180:181], v[180:181], 0, s[28:29]
	s_cmp_ge_u32 s0, s34
	v_lshl_add_u64 v[82:83], v[190:191], 0, s[28:29]
	v_lshl_add_u64 v[84:85], v[192:193], 0, s[28:29]
	s_mov_b32 s36, s1
	s_cbranch_scc0 .LBB0_167
	s_add_i32 s23, s0, -4
	s_cmp_ge_u32 s23, s34
	s_cbranch_scc1 .LBB0_202
	s_add_i32 s56, s0, -5
; #define WAIT_BAR(N) asm volatile("s_waitcnt vmcnt(" #N ") lgkmcnt(0)\n\ts_barrier":::"memory")
;   #define RESC() do{ if(resc){ asm volatile("s_waitcnt lgkmcnt(0)":::"memory"); \
;       _Pragma("unroll") for(int d_=0;d_<2;++d_) _Pragma("unroll") for(int r=0;r<16;++r)o[d_][r]*=wsf[crow(r,hi)]; } }while(0)
;   #define ROT() do{sl_prev=sl_cur;sl_cur=sl_next;sl_next=(sl_next==(NSLOT-1)*SLOTB)?0:sl_next+SLOTB;}while(0)
;   #define ENDW(tt) do{ if((tt)+3<NT){WAIT_BAR(2);} else if((tt)+2<NT){WAIT_BAR(1);} else {WAIT_BAR(0);} }while(0)
; template<int THRL> __device__ __forceinline__ void attn_unit(int S,int b,int h,int qb,const bf16*Q,const bf16*__restrict__ K,const bf16*__restrict__ V,bf16*O,char*shm,const float mref){
;     ...
;   int t=1;
;     ...
;   for(;t+5<NT;t+=2){
;     STEP(pB0,pB1,pA0,pA1,t,true,true,true);     WAIT_BAR(2); RESC(); ROT();
;     STEP(pA0,pA1,pB0,pB1,t+1,true,true,true);   WAIT_BAR(2); RESC(); ROT();
;   }
;     ...
;   for(;t+1<NT;t+=2){
;     STEP(pB0,pB1,pA0,pA1,t,(t+3<NT),(t+1<NT),(t+1<NT));       ENDW(t);   RESC(); ROT();
;     STEP(pA0,pA1,pB0,pB1,t+1,(t+4<NT),(t+2<NT),(t+2<NT));     ENDW(t+1); RESC(); ROT();
.LBB0_170:
	v_add_u32_e32 v186, s1, v212
	ds_read_b64_tr_b16 v[182:183], v186 offset:24576
	ds_read_b64_tr_b16 v[184:185], v186 offset:25088
	v_add_f32_e32 v82, v66, v67
	s_waitcnt lgkmcnt(9)
	v_mfma_f32_32x32x16_bf16 v[98:113], v[174:177], v[134:137], v[34:49]
	v_add_f32_e32 v82, v68, v82
	v_add_f32_e32 v82, v69, v82
	v_add_f32_e32 v82, v70, v82
	v_add_f32_e32 v122, v71, v82
	v_cvt_pk_bf16_f32 v142, v66, v67
	v_cvt_pk_bf16_f32 v143, v68, v69
	ds_read_b64_tr_b16 v[174:175], v186 offset:28672
	ds_read_b64_tr_b16 v[176:177], v186 offset:29184
	s_waitcnt lgkmcnt(10)
	v_mfma_f32_32x32x16_bf16 v[82:97], v[170:173], v[134:137], v[34:49]
	v_add_f32_e32 v66, v72, v122
	v_add_f32_e32 v66, v73, v66
	v_add_f32_e32 v66, v74, v66
	v_add_f32_e32 v66, v75, v66
	v_cvt_pk_bf16_f32 v144, v70, v71
	v_cvt_pk_bf16_f32 v145, v72, v73
	ds_read_b64_tr_b16 v[178:179], v186 offset:25600
	ds_read_b64_tr_b16 v[180:181], v186 offset:26112
	s_waitcnt lgkmcnt(11)
	v_mfma_f32_32x32x16_bf16 v[98:113], v[166:169], v[126:129], v[98:113]
	v_add_f32_e32 v66, v76, v66
	v_add_f32_e32 v66, v77, v66
	v_add_f32_e32 v66, v78, v66
	v_add_f32_e32 v66, v79, v66
	v_cvt_pk_bf16_f32 v138, v74, v75
	v_cvt_pk_bf16_f32 v139, v76, v77
	ds_read_b64_tr_b16 v[74:75], v186 offset:29696
	ds_read_b64_tr_b16 v[76:77], v186 offset:30208
	s_waitcnt lgkmcnt(12)
	v_mfma_f32_32x32x16_bf16 v[82:97], v[162:165], v[126:129], v[82:97]
	v_add_f32_e32 v66, v80, v66
	v_add_f32_e32 v66, v81, v66
	v_add_f32_e32 v66, v50, v66
	v_add_f32_e32 v66, v51, v66
	v_cvt_pk_bf16_f32 v140, v78, v79
	v_cvt_pk_bf16_f32 v141, v80, v81
	ds_read_b64_tr_b16 v[70:71], v186 offset:26624
	ds_read_b64_tr_b16 v[72:73], v186 offset:27136
	s_waitcnt lgkmcnt(13)
	v_mfma_f32_32x32x16_bf16 v[98:113], v[158:161], v[118:121], v[98:113]
	v_add_f32_e32 v66, v52, v66
	v_add_f32_e32 v66, v53, v66
	v_add_f32_e32 v66, v54, v66
	v_add_f32_e32 v78, v55, v66
	v_cvt_pk_bf16_f32 v130, v50, v51
	v_cvt_pk_bf16_f32 v131, v52, v53
	ds_read_b64_tr_b16 v[66:67], v186 offset:30720
	ds_read_b64_tr_b16 v[68:69], v186 offset:31232
	s_waitcnt lgkmcnt(14)
	v_mfma_f32_32x32x16_bf16 v[82:97], v[154:157], v[118:121], v[82:97]
	v_add_f32_e32 v50, v56, v78
	v_add_f32_e32 v50, v57, v50
	v_add_f32_e32 v50, v58, v50
	v_add_f32_e32 v50, v59, v50
	v_cvt_pk_bf16_f32 v132, v54, v55
	v_cvt_pk_bf16_f32 v133, v56, v57
	ds_read_b64_tr_b16 v[54:55], v186 offset:27648
	ds_read_b64_tr_b16 v[56:57], v186 offset:28160
	s_waitcnt lgkmcnt(14)
	v_mfma_f32_32x32x16_bf16 v[98:113], v[150:153], v[114:117], v[98:113]
	v_add_f32_e32 v50, v60, v50
	v_add_f32_e32 v50, v61, v50
	v_add_f32_e32 v50, v62, v50
	v_add_f32_e32 v78, v63, v50
	v_cvt_pk_bf16_f32 v122, v58, v59
	v_cvt_pk_bf16_f32 v123, v60, v61
	ds_read_b64_tr_b16 v[50:51], v186 offset:31744
	ds_read_b64_tr_b16 v[52:53], v186 offset:32256
	v_mfma_f32_32x32x16_bf16 v[82:97], v[146:149], v[114:117], v[82:97]
	v_add_f32_e32 v58, v64, v78
	v_add_f32_e32 v58, v65, v58
	v_add_f32_e32 v214, 0, v58
	v_cvt_pk_bf16_f32 v124, v62, v63
	v_cvt_pk_bf16_f32 v125, v64, v65
	s_add_i32 s0, s55, 1
	s_cmp_ge_u32 s0, s34
	s_cselect_b64 s[36:37], -1, 0
	s_and_b64 vcc, exec, s[36:37]
	s_cbranch_vccnz .LBB0_172
	v_lshl_add_u64 v[58:59], v[192:193], 0, s[74:75]
	s_add_i32 s0, s53, s51
	s_mov_b32 s1, m0
	s_mov_b32 m0, s0
	s_nop 0
	global_load_lds_dwordx4 v[58:59], off
	s_mov_b32 m0, s1
.LBB0_172:
	s_add_i32 s0, s54, s52
	s_mov_b32 s1, m0
	s_mov_b32 m0, s0
	s_nop 0
	global_load_lds_dwordx4 v[190:191], off
	s_mov_b32 m0, s1
	s_waitcnt lgkmcnt(14)
	v_mfma_f32_32x32x16_bf16 v[2:17], v[142:145], v[182:185], v[2:17]
	v_exp_f32_e32 v98, v98
	v_exp_f32_e32 v99, v99
	v_exp_f32_e32 v100, v100
	v_exp_f32_e32 v101, v101
	s_waitcnt lgkmcnt(12)
	v_mfma_f32_32x32x16_bf16 v[18:33], v[142:145], v[174:177], v[18:33]
	v_exp_f32_e32 v102, v102
	v_exp_f32_e32 v103, v103
	v_exp_f32_e32 v104, v104
	v_exp_f32_e32 v105, v105
	v_add_u32_e32 v58, s54, v213
	ds_read_b128 v[174:177], v58
	ds_read_b128 v[170:173], v58 offset:512
	s_waitcnt lgkmcnt(12)
	v_mfma_f32_32x32x16_bf16 v[2:17], v[138:141], v[178:181], v[2:17]
	v_exp_f32_e32 v106, v106
	v_exp_f32_e32 v107, v107
	v_exp_f32_e32 v108, v108
	v_exp_f32_e32 v109, v109
	ds_read_b128 v[166:169], v58 offset:2048
	ds_read_b128 v[162:165], v58 offset:2560
	s_waitcnt lgkmcnt(12)
	v_mfma_f32_32x32x16_bf16 v[18:33], v[138:141], v[74:77], v[18:33]
	v_exp_f32_e32 v110, v110
	v_exp_f32_e32 v111, v111
	v_exp_f32_e32 v112, v112
	v_exp_f32_e32 v113, v113
	ds_read_b128 v[158:161], v58 offset:4096
	ds_read_b128 v[154:157], v58 offset:4608
	s_waitcnt lgkmcnt(12)
	v_mfma_f32_32x32x16_bf16 v[2:17], v[130:133], v[70:73], v[2:17]
	v_exp_f32_e32 v82, v82
	v_exp_f32_e32 v83, v83
	v_exp_f32_e32 v84, v84
	v_exp_f32_e32 v85, v85
	ds_read_b128 v[150:153], v58 offset:6144
	ds_read_b128 v[146:149], v58 offset:6656
	s_waitcnt lgkmcnt(12)
	v_mfma_f32_32x32x16_bf16 v[18:33], v[130:133], v[66:69], v[18:33]
	v_exp_f32_e32 v86, v86
	v_exp_f32_e32 v87, v87
	v_exp_f32_e32 v88, v88
	v_exp_f32_e32 v89, v89
	s_waitcnt lgkmcnt(10)
	v_mfma_f32_32x32x16_bf16 v[2:17], v[122:125], v[54:57], v[2:17]
	v_exp_f32_e32 v90, v90
	v_exp_f32_e32 v91, v91
	v_exp_f32_e32 v92, v92
	v_exp_f32_e32 v93, v93
	s_waitcnt lgkmcnt(8)
	v_mfma_f32_32x32x16_bf16 v[18:33], v[122:125], v[50:53], v[18:33]
	v_exp_f32_e32 v94, v94
	v_exp_f32_e32 v95, v95
	v_exp_f32_e32 v96, v96
	v_exp_f32_e32 v97, v97
	s_mov_b64 s[0:1], -1
	s_and_b64 vcc, exec, s[36:37]
	s_cbranch_vccz .LBB0_178
	s_cmp_ge_u32 s55, s34
	s_cbranch_scc0 .LBB0_175
	s_waitcnt vmcnt(0) lgkmcnt(0)
	s_barrier
	s_mov_b64 s[0:1], 0

; #define WAIT_BAR(N) asm volatile("s_waitcnt vmcnt(" #N ") lgkmcnt(0)\n\ts_barrier":::"memory")
;   #define RESC() do{ if(resc){ asm volatile("s_waitcnt lgkmcnt(0)":::"memory"); \
;       _Pragma("unroll") for(int d_=0;d_<2;++d_) _Pragma("unroll") for(int r=0;r<16;++r)o[d_][r]*=wsf[crow(r,hi)]; } }while(0)
;   #define ROT() do{sl_prev=sl_cur;sl_cur=sl_next;sl_next=(sl_next==(NSLOT-1)*SLOTB)?0:sl_next+SLOTB;}while(0)
;   #define ENDW(tt) do{ if((tt)+3<NT){WAIT_BAR(2);} else if((tt)+2<NT){WAIT_BAR(1);} else {WAIT_BAR(0);} }while(0)
; template<int THRL> __device__ __forceinline__ void attn_unit(int S,int b,int h,int qb,const bf16*Q,const bf16*__restrict__ K,const bf16*__restrict__ V,bf16*O,char*shm,const float mref){
;     ...
;   int t=1;
;     ...
;   for(;t+5<NT;t+=2){
;     STEP(pB0,pB1,pA0,pA1,t,true,true,true);     WAIT_BAR(2); RESC(); ROT();
;     STEP(pA0,pA1,pB0,pB1,t+1,true,true,true);   WAIT_BAR(2); RESC(); ROT();
;   }
;     ...
;   for(;t+1<NT;t+=2){
;     STEP(pB0,pB1,pA0,pA1,t,(t+3<NT),(t+1<NT),(t+1<NT));       ENDW(t);   RESC(); ROT();
;     STEP(pA0,pA1,pB0,pB1,t+1,(t+4<NT),(t+2<NT),(t+2<NT));     ENDW(t+1); RESC(); ROT();
.LBB0_180:
	v_add_u32_e32 v204, s53, v212
	ds_read_b64_tr_b16 v[186:187], v204 offset:24576
	ds_read_b64_tr_b16 v[188:189], v204 offset:25088
	v_add_f32_e32 v50, v98, v99
	s_waitcnt lgkmcnt(9)
	v_mfma_f32_32x32x16_bf16 v[66:81], v[174:177], v[134:137], v[34:49]
	v_add_f32_e32 v50, v100, v50
	v_add_f32_e32 v50, v101, v50
	v_add_f32_e32 v50, v102, v50
	v_add_f32_e32 v122, v103, v50
	v_cvt_pk_bf16_f32 v142, v98, v99
	v_cvt_pk_bf16_f32 v143, v100, v101
	ds_read_b64_tr_b16 v[182:183], v204 offset:28672
	ds_read_b64_tr_b16 v[184:185], v204 offset:29184
	s_waitcnt lgkmcnt(10)
	v_mfma_f32_32x32x16_bf16 v[50:65], v[170:173], v[134:137], v[34:49]
	v_add_f32_e32 v98, v104, v122
	v_add_f32_e32 v98, v105, v98
	v_add_f32_e32 v98, v106, v98
	v_add_f32_e32 v98, v107, v98
	v_cvt_pk_bf16_f32 v144, v102, v103
	v_cvt_pk_bf16_f32 v145, v104, v105
	ds_read_b64_tr_b16 v[178:179], v204 offset:25600
	ds_read_b64_tr_b16 v[180:181], v204 offset:26112
	s_waitcnt lgkmcnt(11)
	v_mfma_f32_32x32x16_bf16 v[66:81], v[166:169], v[126:129], v[66:81]
	v_add_f32_e32 v98, v108, v98
	v_add_f32_e32 v98, v109, v98
	v_add_f32_e32 v98, v110, v98
	v_add_f32_e32 v98, v111, v98
	v_cvt_pk_bf16_f32 v138, v106, v107
	v_cvt_pk_bf16_f32 v139, v108, v109
	ds_read_b64_tr_b16 v[106:107], v204 offset:29696
	ds_read_b64_tr_b16 v[108:109], v204 offset:30208
	s_waitcnt lgkmcnt(12)
	v_mfma_f32_32x32x16_bf16 v[50:65], v[162:165], v[126:129], v[50:65]
	v_add_f32_e32 v98, v112, v98
	v_add_f32_e32 v98, v113, v98
	v_add_f32_e32 v98, v82, v98
	v_add_f32_e32 v98, v83, v98
	v_cvt_pk_bf16_f32 v140, v110, v111
	v_cvt_pk_bf16_f32 v141, v112, v113
	ds_read_b64_tr_b16 v[102:103], v204 offset:26624
	ds_read_b64_tr_b16 v[104:105], v204 offset:27136
	s_waitcnt lgkmcnt(13)
	v_mfma_f32_32x32x16_bf16 v[66:81], v[158:161], v[118:121], v[66:81]
	v_add_f32_e32 v98, v84, v98
	v_add_f32_e32 v98, v85, v98
	v_add_f32_e32 v98, v86, v98
	v_add_f32_e32 v110, v87, v98
	v_cvt_pk_bf16_f32 v130, v82, v83
	v_cvt_pk_bf16_f32 v131, v84, v85
	ds_read_b64_tr_b16 v[98:99], v204 offset:30720
	ds_read_b64_tr_b16 v[100:101], v204 offset:31232
	s_waitcnt lgkmcnt(14)
	v_mfma_f32_32x32x16_bf16 v[50:65], v[154:157], v[118:121], v[50:65]
	v_add_f32_e32 v82, v88, v110
	v_add_f32_e32 v82, v89, v82
	v_add_f32_e32 v82, v90, v82
	v_add_f32_e32 v82, v91, v82
	v_cvt_pk_bf16_f32 v132, v86, v87
	v_cvt_pk_bf16_f32 v133, v88, v89
	ds_read_b64_tr_b16 v[86:87], v204 offset:27648
	ds_read_b64_tr_b16 v[88:89], v204 offset:28160
	s_waitcnt lgkmcnt(14)
	v_mfma_f32_32x32x16_bf16 v[66:81], v[150:153], v[114:117], v[66:81]
	v_add_f32_e32 v82, v92, v82
	v_add_f32_e32 v82, v93, v82
	v_add_f32_e32 v82, v94, v82
	v_add_f32_e32 v110, v95, v82
	v_cvt_pk_bf16_f32 v122, v90, v91
	v_cvt_pk_bf16_f32 v123, v92, v93
	ds_read_b64_tr_b16 v[82:83], v204 offset:31744
	ds_read_b64_tr_b16 v[84:85], v204 offset:32256
	v_mfma_f32_32x32x16_bf16 v[50:65], v[146:149], v[114:117], v[50:65]
	v_add_f32_e32 v90, v96, v110
	v_add_f32_e32 v90, v97, v90
	v_add_f32_e32 v90, 0, v90
	v_cvt_pk_bf16_f32 v124, v94, v95
	v_cvt_pk_bf16_f32 v125, v96, v97
	s_add_i32 s23, s55, 2
	s_cmp_ge_u32 s23, s34
	s_cselect_b64 s[40:41], -1, 0
	s_and_b64 vcc, exec, s[40:41]
	s_cbranch_vccnz .LBB0_182
	s_add_i32 s0, s54, s51
	s_mov_b32 s1, m0
	s_mov_b32 m0, s0
	s_nop 0
	global_load_lds_dwordx4 v[192:193], off
	s_mov_b32 m0, s1

; #define WAIT_BAR(N) asm volatile("s_waitcnt vmcnt(" #N ") lgkmcnt(0)\n\ts_barrier":::"memory")
;   #define RESC() do{ if(resc){ asm volatile("s_waitcnt lgkmcnt(0)":::"memory"); \
;       _Pragma("unroll") for(int d_=0;d_<2;++d_) _Pragma("unroll") for(int r=0;r<16;++r)o[d_][r]*=wsf[crow(r,hi)]; } }while(0)
;   #define ROT() do{sl_prev=sl_cur;sl_cur=sl_next;sl_next=(sl_next==(NSLOT-1)*SLOTB)?0:sl_next+SLOTB;}while(0)
;   #define ENDW(tt) do{ if((tt)+3<NT){WAIT_BAR(2);} else if((tt)+2<NT){WAIT_BAR(1);} else {WAIT_BAR(0);} }while(0)
; template<int THRL> __device__ __forceinline__ void attn_unit(int S,int b,int h,int qb,const bf16*Q,const bf16*__restrict__ K,const bf16*__restrict__ V,bf16*O,char*shm,const float mref){
;     ...
;   int t=1;
;     ...
;   for(;t+5<NT;t+=2){
;     STEP(pB0,pB1,pA0,pA1,t,true,true,true);     WAIT_BAR(2); RESC(); ROT();
;     STEP(pA0,pA1,pB0,pB1,t+1,true,true,true);   WAIT_BAR(2); RESC(); ROT();
;   }
;     ...
;   for(;t+1<NT;t+=2){
;     STEP(pB0,pB1,pA0,pA1,t,(t+3<NT),(t+1<NT),(t+1<NT));       ENDW(t);   RESC(); ROT();
;     STEP(pA0,pA1,pB0,pB1,t+1,(t+4<NT),(t+2<NT),(t+2<NT));     ENDW(t+1); RESC(); ROT();
.LBB0_184:
	s_waitcnt lgkmcnt(14)
	v_mfma_f32_32x32x16_bf16 v[2:17], v[142:145], v[186:189], v[2:17]
	v_exp_f32_e32 v66, v66
	v_exp_f32_e32 v67, v67
	v_exp_f32_e32 v68, v68
	v_exp_f32_e32 v69, v69
	s_waitcnt lgkmcnt(12)
	v_mfma_f32_32x32x16_bf16 v[18:33], v[142:145], v[182:185], v[18:33]
	v_exp_f32_e32 v70, v70
	v_exp_f32_e32 v71, v71
	v_exp_f32_e32 v72, v72
	v_exp_f32_e32 v73, v73
	v_cndmask_b32_e64 v91, 0, 1, s[44:45]
	v_cmp_ne_u32_e64 s[0:1], 1, v91
	s_andn2_b64 vcc, exec, s[44:45]
	v_add_u32_e32 v91, s53, v213
	s_cbranch_vccnz .LBB0_186
	ds_read_b128 v[174:177], v91
	ds_read_b128 v[170:173], v91 offset:512
.LBB0_186:
	s_waitcnt lgkmcnt(10)
	v_mfma_f32_32x32x16_bf16 v[2:17], v[138:141], v[178:181], v[2:17]
	v_exp_f32_e32 v74, v74
	v_exp_f32_e32 v75, v75
	v_exp_f32_e32 v76, v76
	v_exp_f32_e32 v77, v77
	s_and_b64 vcc, exec, s[0:1]
	s_cbranch_vccnz .LBB0_188
	ds_read_b128 v[166:169], v91 offset:2048
	ds_read_b128 v[162:165], v91 offset:2560
.LBB0_188:
	s_waitcnt lgkmcnt(8)
	v_mfma_f32_32x32x16_bf16 v[18:33], v[138:141], v[106:109], v[18:33]
	v_exp_f32_e32 v78, v78
	v_exp_f32_e32 v79, v79
	v_exp_f32_e32 v80, v80
	v_exp_f32_e32 v81, v81
	s_and_b64 vcc, exec, s[0:1]
	s_cbranch_vccnz .LBB0_190
	ds_read_b128 v[158:161], v91 offset:4096
	ds_read_b128 v[154:157], v91 offset:4608
.LBB0_190:
	s_waitcnt lgkmcnt(6)
	v_mfma_f32_32x32x16_bf16 v[2:17], v[130:133], v[102:105], v[2:17]
	v_exp_f32_e32 v50, v50
	v_exp_f32_e32 v51, v51
	v_exp_f32_e32 v52, v52
	v_exp_f32_e32 v53, v53
	s_and_b64 vcc, exec, s[0:1]
	s_cbranch_vccnz .LBB0_192
	ds_read_b128 v[150:153], v91 offset:6144
	ds_read_b128 v[146:149], v91 offset:6656
.LBB0_192:
	s_waitcnt lgkmcnt(4)
	v_mfma_f32_32x32x16_bf16 v[18:33], v[130:133], v[98:101], v[18:33]
	v_exp_f32_e32 v54, v54
	v_exp_f32_e32 v55, v55
	v_exp_f32_e32 v56, v56
	v_exp_f32_e32 v57, v57
	s_waitcnt lgkmcnt(2)
	v_mfma_f32_32x32x16_bf16 v[2:17], v[122:125], v[86:89], v[2:17]
	v_exp_f32_e32 v58, v58
	v_exp_f32_e32 v59, v59
	v_exp_f32_e32 v60, v60
	v_exp_f32_e32 v61, v61
	s_waitcnt lgkmcnt(0)
	v_mfma_f32_32x32x16_bf16 v[18:33], v[122:125], v[82:85], v[18:33]
	v_exp_f32_e32 v62, v62
	v_exp_f32_e32 v63, v63
	v_exp_f32_e32 v64, v64
	v_exp_f32_e32 v65, v65
	s_mov_b64 s[0:1], -1
	s_and_b64 vcc, exec, s[40:41]
	s_cbranch_vccz .LBB0_198
	s_and_b64 vcc, exec, s[36:37]
	s_cbranch_vccz .LBB0_195
	s_waitcnt vmcnt(0) lgkmcnt(0)
	s_barrier
	s_mov_b64 s[0:1], 0

;   #define RESC() do{ if(resc){ asm volatile("s_waitcnt lgkmcnt(0)":::"memory"); \
;       _Pragma("unroll") for(int d_=0;d_<2;++d_) _Pragma("unroll") for(int r=0;r<16;++r)o[d_][r]*=wsf[crow(r,hi)]; } }while(0)
; template<int THRL> __device__ __forceinline__ void attn_unit(int S,int b,int h,int qb,const bf16*Q,const bf16*__restrict__ K,const bf16*__restrict__ V,bf16*O,char*shm,const float mref){
;     ...
;   STEP(pB0,pB1,pA0,pA1,NT-1,false,false,false); RESC();
;   { float sacc=pB0[0]+pB0[1]; _Pragma("unroll") for(int r=2;r<16;++r)sacc+=pB0[r]; _Pragma("unroll") for(int r=0;r<16;++r)sacc+=pB1[r]; l_reg+=sacc;
.LBB0_203:
	s_and_b32 s0, s50, 0x3fffffc0
	s_cmp_lg_u32 0, -1
	s_cselect_b32 s1, 0, 0
	s_lshl_b32 s0, s0, 2
	s_addk_i32 s1, 0x6000
	s_add_i32 s36, s0, 0
	v_add3_u32 v102, v211, s1, v210
	v_add_u32_e32 v103, s54, v212
	ds_read_b64_tr_b16 v[98:99], v103 offset:24576
	ds_read_b64_tr_b16 v[100:101], v103 offset:25088
	v_add_f32_e32 v104, v66, v67
	s_waitcnt lgkmcnt(9)
	v_mfma_f32_32x32x16_bf16 v[82:97], v[174:177], v[134:137], v[34:49]
	v_add_f32_e32 v104, v68, v104
	v_add_f32_e32 v104, v69, v104
	v_add_f32_e32 v104, v70, v104
	v_add_f32_e32 v104, v71, v104
	v_cvt_pk_bf16_f32 v142, v66, v67
	v_cvt_pk_bf16_f32 v143, v68, v69
	ds_read_b64_tr_b16 v[66:67], v103 offset:28672
	ds_read_b64_tr_b16 v[68:69], v103 offset:29184
	s_waitcnt lgkmcnt(10)
	v_mfma_f32_32x32x16_bf16 v[34:49], v[170:173], v[134:137], v[34:49]
	v_add_f32_e32 v104, v72, v104
	v_add_f32_e32 v104, v73, v104
	v_add_f32_e32 v104, v74, v104
	v_add_f32_e32 v104, v75, v104
	v_cvt_pk_bf16_f32 v144, v70, v71
	v_cvt_pk_bf16_f32 v145, v72, v73
	ds_read_b64_tr_b16 v[70:71], v103 offset:25600
	ds_read_b64_tr_b16 v[72:73], v103 offset:26112
	s_waitcnt lgkmcnt(11)
	v_mfma_f32_32x32x16_bf16 v[82:97], v[166:169], v[126:129], v[82:97]
	v_add_f32_e32 v104, v76, v104
	v_add_f32_e32 v104, v77, v104
	v_add_f32_e32 v104, v78, v104
	v_add_f32_e32 v104, v79, v104
	v_cvt_pk_bf16_f32 v138, v74, v75
	v_cvt_pk_bf16_f32 v139, v76, v77
	ds_read_b64_tr_b16 v[74:75], v103 offset:29696
	ds_read_b64_tr_b16 v[76:77], v103 offset:30208
	s_waitcnt lgkmcnt(12)
	v_mfma_f32_32x32x16_bf16 v[34:49], v[162:165], v[126:129], v[34:49]
	v_add_f32_e32 v104, v80, v104
	v_add_f32_e32 v104, v81, v104
	v_add_f32_e32 v104, v50, v104
	v_add_f32_e32 v104, v51, v104
	v_cvt_pk_bf16_f32 v140, v78, v79
	v_cvt_pk_bf16_f32 v141, v80, v81
	ds_read_b64_tr_b16 v[78:79], v103 offset:26624
	ds_read_b64_tr_b16 v[80:81], v103 offset:27136
	s_waitcnt lgkmcnt(13)
	v_mfma_f32_32x32x16_bf16 v[82:97], v[158:161], v[118:121], v[82:97]
	v_add_f32_e32 v104, v52, v104
	v_add_f32_e32 v104, v53, v104
	v_add_f32_e32 v104, v54, v104
	v_add_f32_e32 v104, v55, v104
	v_cvt_pk_bf16_f32 v130, v50, v51
	v_cvt_pk_bf16_f32 v131, v52, v53
	ds_read_b64_tr_b16 v[50:51], v103 offset:30720
	ds_read_b64_tr_b16 v[52:53], v103 offset:31232
	s_waitcnt lgkmcnt(14)
	v_mfma_f32_32x32x16_bf16 v[34:49], v[154:157], v[118:121], v[34:49]
	v_add_f32_e32 v104, v56, v104
	v_add_f32_e32 v104, v57, v104
	v_add_f32_e32 v104, v58, v104
	v_add_f32_e32 v104, v59, v104
	v_cvt_pk_bf16_f32 v132, v54, v55
	v_cvt_pk_bf16_f32 v133, v56, v57
	ds_read_b64_tr_b16 v[54:55], v103 offset:27648
	ds_read_b64_tr_b16 v[56:57], v103 offset:28160
	s_waitcnt lgkmcnt(14)
	v_mfma_f32_32x32x16_bf16 v[82:97], v[150:153], v[114:117], v[82:97]
	v_add_f32_e32 v104, v60, v104
	v_add_f32_e32 v104, v61, v104
	v_add_f32_e32 v104, v62, v104
	v_add_f32_e32 v104, v63, v104
	v_cvt_pk_bf16_f32 v122, v58, v59
	v_cvt_pk_bf16_f32 v123, v60, v61
	ds_read_b64_tr_b16 v[58:59], v103 offset:31744
	ds_read_b64_tr_b16 v[60:61], v103 offset:32256
	v_mfma_f32_32x32x16_bf16 v[34:49], v[146:149], v[114:117], v[34:49]
	v_add_f32_e32 v103, v64, v104
	v_add_f32_e32 v103, v65, v103
	v_add_f32_e32 v103, 0, v103
	v_cvt_pk_bf16_f32 v124, v62, v63
	v_cvt_pk_bf16_f32 v125, v64, v65
	s_waitcnt lgkmcnt(14)
	v_mfma_f32_32x32x16_bf16 v[2:17], v[142:145], v[98:101], v[2:17]
	v_exp_f32_e32 v82, v82
	v_exp_f32_e32 v83, v83
	v_exp_f32_e32 v84, v84
	v_exp_f32_e32 v85, v85
	s_waitcnt lgkmcnt(12)
	v_mfma_f32_32x32x16_bf16 v[18:33], v[142:145], v[66:69], v[18:33]
	v_exp_f32_e32 v86, v86
	v_exp_f32_e32 v87, v87
	v_exp_f32_e32 v88, v88
	v_exp_f32_e32 v89, v89
	s_waitcnt lgkmcnt(10)
	v_mfma_f32_32x32x16_bf16 v[2:17], v[138:141], v[70:73], v[2:17]
	v_exp_f32_e32 v90, v90
	v_exp_f32_e32 v91, v91
	v_exp_f32_e32 v92, v92
	v_exp_f32_e32 v93, v93
	s_waitcnt lgkmcnt(8)
; #define SBAR() __builtin_amdgcn_sched_barrier(0)
;   #define RESC() do{ if(resc){ asm volatile("s_waitcnt lgkmcnt(0)":::"memory"); \
;       _Pragma("unroll") for(int d_=0;d_<2;++d_) _Pragma("unroll") for(int r=0;r<16;++r)o[d_][r]*=wsf[crow(r,hi)]; } }while(0)
;   #define PKW(P,B) cvtpk_s(P[B],P[B+1])
; __device__ __forceinline__ void pv(f32x16*o,int vb,bf16x8 pa0,bf16x8 pa1,bf16x8 pa2,bf16x8 pa3){
;   #pragma unroll
;   for(int d0=0;d0<2;++d0){s16x4 lo[4],hi[4];
;     #pragma unroll
;     for(int ks=0;ks<4;++ks){
;       asm volatile("ds_read_b64_tr_b16 %0,%1 offset:%c2":"=&v"(lo[ks]):"v"(vb),"i"(d0*4096+ks*1024):"memory");
;       asm volatile("ds_read_b64_tr_b16 %0,%1 offset:%c2":"=&v"(hi[ks]):"v"(vb),"i"(d0*4096+ks*1024+512):"memory");}
;     asm volatile("s_waitcnt lgkmcnt(0)":::"memory");SBAR();
;     ...
;     o[d0]=__builtin_amdgcn_mfma_f32_32x32x16_bf16(pa0,PK(0),o[d0],0,0,0);
;     o[d0]=__builtin_amdgcn_mfma_f32_32x32x16_bf16(pa1,PK(1),o[d0],0,0,0);
;     o[d0]=__builtin_amdgcn_mfma_f32_32x32x16_bf16(pa2,PK(2),o[d0],0,0,0);
;     o[d0]=__builtin_amdgcn_mfma_f32_32x32x16_bf16(pa3,PK(3),o[d0],0,0,0);
;     ...
;   }
; template<int THRL> __device__ __forceinline__ void attn_unit(int S,int b,int h,int qb,const bf16*Q,const bf16*__restrict__ K,const bf16*__restrict__ V,bf16*O,char*shm,const float mref){
;     ...
;   STEP(pB0,pB1,pA0,pA1,NT-1,false,false,false); RESC();
;   { float sacc=pB0[0]+pB0[1]; _Pragma("unroll") for(int r=2;r<16;++r)sacc+=pB0[r]; _Pragma("unroll") for(int r=0;r<16;++r)sacc+=pB1[r]; l_reg+=sacc;
;     pw0=(u32x4){PKW(pB0,0),PKW(pB0,2),PKW(pB0,4),PKW(pB0,6)};pw1=(u32x4){PKW(pB0,8),PKW(pB0,10),PKW(pB0,12),PKW(pB0,14)};pw2=(u32x4){PKW(pB1,0),PKW(pB1,2),PKW(pB1,4),PKW(pB1,6)};pw3=(u32x4){PKW(pB1,8),PKW(pB1,10),PKW(pB1,12),PKW(pB1,14)};
;     SBAR(); pv(o,vb0+sl_cur,PAF(0),PAF(1),PAF(2),PAF(3)); }
;     ...
;   {auto rr=__builtin_amdgcn_permlane32_swap(__float_as_uint(l_reg),__float_as_uint(l_reg),false,false);l_reg=__uint_as_float(rr[0])+__uint_as_float(rr[1]);}
;   if(hi==0)wsf[32+r32]=l_reg;asm volatile("s_waitcnt lgkmcnt(0)":::"memory");
	v_mfma_f32_32x32x16_bf16 v[18:33], v[138:141], v[74:77], v[18:33]
	v_exp_f32_e32 v94, v94
	v_exp_f32_e32 v95, v95
	v_exp_f32_e32 v96, v96
	v_exp_f32_e32 v97, v97
	s_waitcnt lgkmcnt(6)
	v_mfma_f32_32x32x16_bf16 v[2:17], v[130:133], v[78:81], v[2:17]
	v_exp_f32_e32 v34, v34
	v_exp_f32_e32 v35, v35
	v_exp_f32_e32 v36, v36
	v_exp_f32_e32 v37, v37
	s_waitcnt lgkmcnt(4)
	v_mfma_f32_32x32x16_bf16 v[18:33], v[130:133], v[50:53], v[18:33]
	v_exp_f32_e32 v38, v38
	v_exp_f32_e32 v39, v39
	v_exp_f32_e32 v40, v40
	v_exp_f32_e32 v41, v41
	s_waitcnt lgkmcnt(2)
	v_mfma_f32_32x32x16_bf16 v[2:17], v[122:125], v[54:57], v[2:17]
	v_exp_f32_e32 v42, v42
	v_exp_f32_e32 v43, v43
	v_exp_f32_e32 v44, v44
	v_exp_f32_e32 v45, v45
	s_waitcnt lgkmcnt(0)
	v_mfma_f32_32x32x16_bf16 v[18:33], v[122:125], v[58:61], v[18:33]
	v_exp_f32_e32 v46, v46
	v_exp_f32_e32 v47, v47
	v_exp_f32_e32 v48, v48
	v_exp_f32_e32 v49, v49
	v_add_f32_e32 v50, v82, v83
	v_add_f32_e32 v50, v84, v50
	v_add_f32_e32 v50, v85, v50
	v_add_f32_e32 v50, v86, v50
	v_add_f32_e32 v50, v87, v50
	v_add_f32_e32 v50, v88, v50
	v_add_f32_e32 v50, v89, v50
	v_add_f32_e32 v50, v90, v50
	v_add_f32_e32 v50, v91, v50
	v_add_f32_e32 v50, v92, v50
	v_add_f32_e32 v50, v93, v50
	v_add_f32_e32 v50, v94, v50
	v_add_f32_e32 v50, v95, v50
	v_add_f32_e32 v50, v96, v50
	v_add_f32_e32 v50, v97, v50
	v_add_f32_e32 v50, v50, v34
	v_add_f32_e32 v50, v35, v50
	v_add_f32_e32 v50, v36, v50
	v_add_f32_e32 v50, v37, v50
	v_add_f32_e32 v50, v38, v50
	v_add_f32_e32 v50, v39, v50
	v_add_f32_e32 v50, v40, v50
	v_add_f32_e32 v50, v41, v50
	v_add_f32_e32 v50, v42, v50
	v_add_f32_e32 v50, v43, v50
	v_add_f32_e32 v50, v44, v50
	v_add_f32_e32 v50, v45, v50
	v_add_f32_e32 v50, v46, v50
	v_add_f32_e32 v50, v47, v50
	v_add_f32_e32 v50, v48, v50
	v_add_f32_e32 v50, v49, v50
	v_add_f32_e32 v51, v201, v103
	v_add_f32_e32 v50, v51, v50
	v_cvt_pk_bf16_f32 v52, v82, v83
	v_cvt_pk_bf16_f32 v53, v84, v85
	v_cvt_pk_bf16_f32 v54, v86, v87
	v_cvt_pk_bf16_f32 v55, v88, v89
	v_cvt_pk_bf16_f32 v56, v90, v91
	v_cvt_pk_bf16_f32 v57, v92, v93
	v_cvt_pk_bf16_f32 v58, v94, v95
	v_cvt_pk_bf16_f32 v59, v96, v97
	v_cvt_pk_bf16_f32 v34, v34, v35
	v_cvt_pk_bf16_f32 v35, v36, v37
	v_cvt_pk_bf16_f32 v36, v38, v39
	v_cvt_pk_bf16_f32 v37, v40, v41
	v_cvt_pk_bf16_f32 v38, v42, v43
	v_cvt_pk_bf16_f32 v39, v44, v45
	v_cvt_pk_bf16_f32 v40, v46, v47
	v_cvt_pk_bf16_f32 v41, v48, v49
	v_add3_u32 v0, v102, v0, s53
	ds_read_b64_tr_b16 v[42:43],v0 offset:0
	ds_read_b64_tr_b16 v[44:45],v0 offset:512
	ds_read_b64_tr_b16 v[46:47],v0 offset:1024
	ds_read_b64_tr_b16 v[48:49],v0 offset:1536
	ds_read_b64_tr_b16 v[60:61],v0 offset:2048
	ds_read_b64_tr_b16 v[62:63],v0 offset:2560
	ds_read_b64_tr_b16 v[64:65],v0 offset:3072
	ds_read_b64_tr_b16 v[66:67],v0 offset:3584
	s_waitcnt lgkmcnt(0)
	s_nop 0
	v_mfma_f32_32x32x16_bf16 v[2:17], v[52:55], v[42:45], v[2:17]
	ds_read_b64_tr_b16 v[42:43],v0 offset:4096
	ds_read_b64_tr_b16 v[44:45],v0 offset:4608
	v_mfma_f32_32x32x16_bf16 v[2:17], v[56:59], v[46:49], v[2:17]
	ds_read_b64_tr_b16 v[46:47],v0 offset:5120
	ds_read_b64_tr_b16 v[48:49],v0 offset:5632
	v_mfma_f32_32x32x16_bf16 v[2:17], v[34:37], v[60:63], v[2:17]
	ds_read_b64_tr_b16 v[60:61],v0 offset:6144
	ds_read_b64_tr_b16 v[62:63],v0 offset:6656
	v_mfma_f32_32x32x16_bf16 v[2:17], v[38:41], v[64:67], v[2:17]
	ds_read_b64_tr_b16 v[64:65],v0 offset:7168
	ds_read_b64_tr_b16 v[66:67],v0 offset:7680
	s_waitcnt lgkmcnt(0)
	v_mfma_f32_32x32x16_bf16 v[18:33], v[52:55], v[42:45], v[18:33]
	v_mov_b32_e32 v0, v50
	s_nop 1
	v_permlane32_swap_b32_e32 v50, v0
	v_cmp_gt_u32_e32 vcc, 32, v197
	v_mfma_f32_32x32x16_bf16 v[18:33], v[56:59], v[46:49], v[18:33]
	v_mfma_f32_32x32x16_bf16 v[18:33], v[34:37], v[60:63], v[18:33]
	v_mfma_f32_32x32x16_bf16 v[18:33], v[38:41], v[64:67], v[18:33]
	s_and_saveexec_b64 s[0:1], vcc
	s_cbranch_execz .LBB0_165
	v_add_f32_e32 v0, v50, v0
	v_lshl_add_u32 v34, v199, 2, s36
	ds_write_b32 v34, v0 offset:49280
	s_branch .LBB0_165

; #define WAIT_BAR(N) asm volatile("s_waitcnt vmcnt(" #N ") lgkmcnt(0)\n\ts_barrier":::"memory")
;   #define RESC() do{ if(resc){ asm volatile("s_waitcnt lgkmcnt(0)":::"memory"); \
;       _Pragma("unroll") for(int d_=0;d_<2;++d_) _Pragma("unroll") for(int r=0;r<16;++r)o[d_][r]*=wsf[crow(r,hi)]; } }while(0)
;   #define ROT() do{sl_prev=sl_cur;sl_cur=sl_next;sl_next=(sl_next==(NSLOT-1)*SLOTB)?0:sl_next+SLOTB;}while(0)
; template<int THRL> __device__ __forceinline__ void attn_unit(int S,int b,int h,int qb,const bf16*Q,const bf16*__restrict__ K,const bf16*__restrict__ V,bf16*O,char*shm,const float mref){
;     ...
;   int t=1;
;     ...
;   for(;t+5<NT;t+=2){
;     STEP(pB0,pB1,pA0,pA1,t,true,true,true);     WAIT_BAR(2); RESC(); ROT();
;     STEP(pA0,pA1,pB0,pB1,t+1,true,true,true);   WAIT_BAR(2); RESC(); ROT();
.LBB0_212:
	s_mov_b32 s40, s48
	s_mov_b32 s0, s35
	v_add_u32_e32 v182, s1, v212
	ds_read_b64_tr_b16 v[184:185], v182 offset:24576
	ds_read_b64_tr_b16 v[186:187], v182 offset:25088
	v_add_f32_e32 v82, v66, v67
	s_waitcnt lgkmcnt(9)
	v_mfma_f32_32x32x16_bf16 v[98:113], v[174:177], v[134:137], v[34:49]
	v_add_f32_e32 v82, v68, v82
	v_add_f32_e32 v82, v69, v82
	v_add_f32_e32 v82, v70, v82
	v_add_f32_e32 v122, v71, v82
	v_cvt_pk_bf16_f32 v142, v66, v67
	v_cvt_pk_bf16_f32 v143, v68, v69
	ds_read_b64_tr_b16 v[66:67], v182 offset:28672
	ds_read_b64_tr_b16 v[68:69], v182 offset:29184
	s_waitcnt lgkmcnt(10)
	v_mfma_f32_32x32x16_bf16 v[82:97], v[170:173], v[134:137], v[34:49]
	v_add_f32_e32 v122, v72, v122
	v_add_f32_e32 v122, v73, v122
	v_add_f32_e32 v122, v74, v122
	v_add_f32_e32 v122, v75, v122
	v_cvt_pk_bf16_f32 v144, v70, v71
	v_cvt_pk_bf16_f32 v145, v72, v73
	ds_read_b64_tr_b16 v[70:71], v182 offset:25600
	ds_read_b64_tr_b16 v[72:73], v182 offset:26112
	s_waitcnt lgkmcnt(11)
	v_mfma_f32_32x32x16_bf16 v[98:113], v[166:169], v[126:129], v[98:113]
	v_add_f32_e32 v122, v76, v122
	v_add_f32_e32 v122, v77, v122
	v_add_f32_e32 v122, v78, v122
	v_add_f32_e32 v122, v79, v122
	v_cvt_pk_bf16_f32 v138, v74, v75
	v_cvt_pk_bf16_f32 v139, v76, v77
	ds_read_b64_tr_b16 v[74:75], v182 offset:29696
	ds_read_b64_tr_b16 v[76:77], v182 offset:30208
	s_waitcnt lgkmcnt(12)
	v_mfma_f32_32x32x16_bf16 v[82:97], v[162:165], v[126:129], v[82:97]
	v_add_f32_e32 v122, v80, v122
	v_add_f32_e32 v122, v81, v122
	v_add_f32_e32 v122, v50, v122
	v_add_f32_e32 v122, v51, v122
	v_cvt_pk_bf16_f32 v140, v78, v79
	v_cvt_pk_bf16_f32 v141, v80, v81
	ds_read_b64_tr_b16 v[78:79], v182 offset:26624
	ds_read_b64_tr_b16 v[80:81], v182 offset:27136
	s_waitcnt lgkmcnt(13)
	v_mfma_f32_32x32x16_bf16 v[98:113], v[158:161], v[118:121], v[98:113]
	v_add_f32_e32 v122, v52, v122
	v_add_f32_e32 v122, v53, v122
	v_add_f32_e32 v122, v54, v122
	v_add_f32_e32 v122, v55, v122
	v_cvt_pk_bf16_f32 v130, v50, v51
	v_cvt_pk_bf16_f32 v131, v52, v53
	ds_read_b64_tr_b16 v[50:51], v182 offset:30720
	ds_read_b64_tr_b16 v[52:53], v182 offset:31232
	s_waitcnt lgkmcnt(14)
	v_mfma_f32_32x32x16_bf16 v[82:97], v[154:157], v[118:121], v[82:97]
	v_add_f32_e32 v122, v56, v122
	v_add_f32_e32 v122, v57, v122
	v_add_f32_e32 v122, v58, v122
	v_add_f32_e32 v122, v59, v122
	v_cvt_pk_bf16_f32 v132, v54, v55
	v_cvt_pk_bf16_f32 v133, v56, v57
	ds_read_b64_tr_b16 v[54:55], v182 offset:27648
	ds_read_b64_tr_b16 v[56:57], v182 offset:28160
	s_waitcnt lgkmcnt(14)
	v_mfma_f32_32x32x16_bf16 v[98:113], v[150:153], v[114:117], v[98:113]
	v_add_f32_e32 v122, v60, v122
	v_add_f32_e32 v122, v61, v122
	v_add_f32_e32 v122, v62, v122
	v_add_f32_e32 v150, v63, v122
	v_cvt_pk_bf16_f32 v122, v58, v59
	v_cvt_pk_bf16_f32 v123, v60, v61
	ds_read_b64_tr_b16 v[58:59], v182 offset:31744
	ds_read_b64_tr_b16 v[60:61], v182 offset:32256
	v_mfma_f32_32x32x16_bf16 v[82:97], v[146:149], v[114:117], v[82:97]
	v_add_f32_e32 v124, v64, v150
	v_add_f32_e32 v124, v65, v124
	v_add_f32_e32 v182, 0, v124
	v_cvt_pk_bf16_f32 v124, v62, v63
	v_cvt_pk_bf16_f32 v125, v64, v65
	v_lshl_add_u64 v[62:63], v[180:181], 0, s[74:75]
	s_add_i32 s1, s35, s44
	s_mov_b32 s23, m0
	s_mov_b32 m0, s1
	s_nop 0
	global_load_lds_dwordx4 v[62:63], off
	s_mov_b32 m0, s23
	v_lshl_add_u64 v[62:63], v[178:179], 0, s[74:75]
	s_add_i32 s1, s48, s34
	s_mov_b32 s23, m0
	s_mov_b32 m0, s1
	s_nop 0
	global_load_lds_dwordx4 v[62:63], off
	s_mov_b32 m0, s23
	s_waitcnt lgkmcnt(14)
	v_mfma_f32_32x32x16_bf16 v[2:17], v[142:145], v[184:187], v[2:17]
	v_exp_f32_e32 v98, v98
	v_exp_f32_e32 v99, v99
	v_exp_f32_e32 v100, v100
	v_exp_f32_e32 v101, v101
	s_waitcnt lgkmcnt(12)
	v_mfma_f32_32x32x16_bf16 v[18:33], v[142:145], v[66:69], v[18:33]
	v_exp_f32_e32 v102, v102
	v_exp_f32_e32 v103, v103
	v_exp_f32_e32 v104, v104
	v_exp_f32_e32 v105, v105
	v_add_u32_e32 v66, s40, v213
	ds_read_b128 v[62:65], v66
	ds_read_b128 v[146:149], v66 offset:512
	s_waitcnt lgkmcnt(12)
	v_mfma_f32_32x32x16_bf16 v[2:17], v[138:141], v[70:73], v[2:17]
	v_exp_f32_e32 v106, v106
	v_exp_f32_e32 v107, v107
	v_exp_f32_e32 v108, v108
	v_exp_f32_e32 v109, v109
	ds_read_b128 v[150:153], v66 offset:2048
	ds_read_b128 v[154:157], v66 offset:2560
	s_waitcnt lgkmcnt(12)
	v_mfma_f32_32x32x16_bf16 v[18:33], v[138:141], v[74:77], v[18:33]
	v_exp_f32_e32 v110, v110
	v_exp_f32_e32 v111, v111
	v_exp_f32_e32 v112, v112
	v_exp_f32_e32 v113, v113
	ds_read_b128 v[158:161], v66 offset:4096
	ds_read_b128 v[162:165], v66 offset:4608
	s_waitcnt lgkmcnt(12)
	v_mfma_f32_32x32x16_bf16 v[2:17], v[130:133], v[78:81], v[2:17]
	v_exp_f32_e32 v82, v82
	v_exp_f32_e32 v83, v83
	v_exp_f32_e32 v84, v84
	v_exp_f32_e32 v85, v85
	ds_read_b128 v[166:169], v66 offset:6144
	ds_read_b128 v[170:173], v66 offset:6656
	s_waitcnt lgkmcnt(12)
	v_mfma_f32_32x32x16_bf16 v[18:33], v[130:133], v[50:53], v[18:33]
	v_exp_f32_e32 v86, v86
	v_exp_f32_e32 v87, v87
	v_exp_f32_e32 v88, v88
	v_exp_f32_e32 v89, v89
	s_waitcnt lgkmcnt(10)
	v_mfma_f32_32x32x16_bf16 v[2:17], v[122:125], v[54:57], v[2:17]
	v_exp_f32_e32 v90, v90
	v_exp_f32_e32 v91, v91
	v_exp_f32_e32 v92, v92
	v_exp_f32_e32 v93, v93
	s_waitcnt lgkmcnt(8)
	v_mfma_f32_32x32x16_bf16 v[18:33], v[122:125], v[58:61], v[18:33]
	v_exp_f32_e32 v94, v94
	v_exp_f32_e32 v95, v95
	v_exp_f32_e32 v96, v96
	v_exp_f32_e32 v97, v97
	s_waitcnt vmcnt(2) lgkmcnt(0)
	s_barrier
; #define WAIT_BAR(N) asm volatile("s_waitcnt vmcnt(" #N ") lgkmcnt(0)\n\ts_barrier":::"memory")
;   #define RESC() do{ if(resc){ asm volatile("s_waitcnt lgkmcnt(0)":::"memory"); \
;       _Pragma("unroll") for(int d_=0;d_<2;++d_) _Pragma("unroll") for(int r=0;r<16;++r)o[d_][r]*=wsf[crow(r,hi)]; } }while(0)
;   #define ROT() do{sl_prev=sl_cur;sl_cur=sl_next;sl_next=(sl_next==(NSLOT-1)*SLOTB)?0:sl_next+SLOTB;}while(0)
; template<int THRL> __device__ __forceinline__ void attn_unit(int S,int b,int h,int qb,const bf16*Q,const bf16*__restrict__ K,const bf16*__restrict__ V,bf16*O,char*shm,const float mref){
;     ...
;   int t=1;
;     ...
;   for(;t+5<NT;t+=2){
;     STEP(pB0,pB1,pA0,pA1,t,true,true,true);     WAIT_BAR(2); RESC(); ROT();
;     STEP(pA0,pA1,pB0,pB1,t+1,true,true,true);   WAIT_BAR(2); RESC(); ROT();
	s_add_i32 s1, s48, 0x2000
	s_cmpk_lg_i32 s48, 0x4000
	s_cselect_b32 s35, s1, 0
	v_add_u32_e32 v183, s0, v212
	ds_read_b64_tr_b16 v[174:175], v183 offset:24576
	ds_read_b64_tr_b16 v[176:177], v183 offset:25088
	v_add_f32_e32 v50, v98, v99
	s_waitcnt lgkmcnt(9)
	v_mfma_f32_32x32x16_bf16 v[66:81], v[62:65], v[134:137], v[34:49]
	v_add_f32_e32 v50, v100, v50
	v_add_f32_e32 v50, v101, v50
	v_add_f32_e32 v50, v102, v50
	v_add_f32_e32 v122, v103, v50
	v_cvt_pk_bf16_f32 v142, v98, v99
	v_cvt_pk_bf16_f32 v143, v100, v101
	ds_read_b64_tr_b16 v[98:99], v183 offset:28672
	ds_read_b64_tr_b16 v[100:101], v183 offset:29184
	s_waitcnt lgkmcnt(10)
	v_mfma_f32_32x32x16_bf16 v[50:65], v[146:149], v[134:137], v[34:49]
	v_add_f32_e32 v122, v104, v122
	v_add_f32_e32 v122, v105, v122
	v_add_f32_e32 v122, v106, v122
	v_add_f32_e32 v122, v107, v122
	v_cvt_pk_bf16_f32 v144, v102, v103
	v_cvt_pk_bf16_f32 v145, v104, v105
	ds_read_b64_tr_b16 v[102:103], v183 offset:25600
	ds_read_b64_tr_b16 v[104:105], v183 offset:26112
	s_waitcnt lgkmcnt(11)
	v_mfma_f32_32x32x16_bf16 v[66:81], v[150:153], v[126:129], v[66:81]
	v_add_f32_e32 v122, v108, v122
	v_add_f32_e32 v122, v109, v122
	v_add_f32_e32 v122, v110, v122
	v_add_f32_e32 v122, v111, v122
	v_cvt_pk_bf16_f32 v138, v106, v107
	v_cvt_pk_bf16_f32 v139, v108, v109
	ds_read_b64_tr_b16 v[106:107], v183 offset:29696
	ds_read_b64_tr_b16 v[108:109], v183 offset:30208
	s_waitcnt lgkmcnt(12)
	v_mfma_f32_32x32x16_bf16 v[50:65], v[154:157], v[126:129], v[50:65]
	v_add_f32_e32 v122, v112, v122
	v_add_f32_e32 v122, v113, v122
	v_add_f32_e32 v122, v82, v122
	v_add_f32_e32 v122, v83, v122
	v_cvt_pk_bf16_f32 v140, v110, v111
	v_cvt_pk_bf16_f32 v141, v112, v113
	ds_read_b64_tr_b16 v[110:111], v183 offset:26624
	ds_read_b64_tr_b16 v[112:113], v183 offset:27136
	s_waitcnt lgkmcnt(13)
	v_mfma_f32_32x32x16_bf16 v[66:81], v[158:161], v[118:121], v[66:81]
	v_add_f32_e32 v122, v84, v122
	v_add_f32_e32 v122, v85, v122
	v_add_f32_e32 v122, v86, v122
	v_add_f32_e32 v122, v87, v122
	v_cvt_pk_bf16_f32 v130, v82, v83
	v_cvt_pk_bf16_f32 v131, v84, v85
	ds_read_b64_tr_b16 v[82:83], v183 offset:30720
	ds_read_b64_tr_b16 v[84:85], v183 offset:31232
	s_waitcnt lgkmcnt(14)
	v_mfma_f32_32x32x16_bf16 v[50:65], v[162:165], v[118:121], v[50:65]
	v_add_f32_e32 v122, v88, v122
	v_add_f32_e32 v122, v89, v122
	v_add_f32_e32 v122, v90, v122
	v_add_f32_e32 v122, v91, v122
	v_cvt_pk_bf16_f32 v132, v86, v87
	v_cvt_pk_bf16_f32 v133, v88, v89
	ds_read_b64_tr_b16 v[86:87], v183 offset:27648
	ds_read_b64_tr_b16 v[88:89], v183 offset:28160
	s_waitcnt lgkmcnt(14)
	v_mfma_f32_32x32x16_bf16 v[66:81], v[166:169], v[114:117], v[66:81]
	v_add_f32_e32 v122, v92, v122
	v_add_f32_e32 v122, v93, v122
	v_add_f32_e32 v122, v94, v122
	v_add_f32_e32 v146, v95, v122
	v_cvt_pk_bf16_f32 v122, v90, v91
	v_cvt_pk_bf16_f32 v123, v92, v93
	ds_read_b64_tr_b16 v[90:91], v183 offset:31744
	ds_read_b64_tr_b16 v[92:93], v183 offset:32256
	v_mfma_f32_32x32x16_bf16 v[50:65], v[170:173], v[114:117], v[50:65]
	v_add_f32_e32 v124, v96, v146
	v_add_f32_e32 v124, v97, v124
	v_add_f32_e32 v183, 0, v124
	v_cvt_pk_bf16_f32 v124, v94, v95
	v_cvt_pk_bf16_f32 v125, v96, v97
	s_add_i32 s0, s48, s44
	s_mov_b32 s1, m0
	s_mov_b32 m0, s0
	s_nop 0
	global_load_lds_dwordx4 v[180:181], off
	s_mov_b32 m0, s1
	s_add_i32 s0, s35, s34
	s_mov_b32 s1, m0
	s_mov_b32 m0, s0
	s_nop 0
	global_load_lds_dwordx4 v[178:179], off
	s_mov_b32 m0, s1
	s_waitcnt lgkmcnt(14)
	v_mfma_f32_32x32x16_bf16 v[2:17], v[142:145], v[174:177], v[2:17]
	v_exp_f32_e32 v66, v66
	v_exp_f32_e32 v67, v67
	v_exp_f32_e32 v68, v68
	v_exp_f32_e32 v69, v69
	s_waitcnt lgkmcnt(12)
	v_mfma_f32_32x32x16_bf16 v[18:33], v[142:145], v[98:101], v[18:33]
	v_exp_f32_e32 v70, v70
	v_exp_f32_e32 v71, v71
	v_exp_f32_e32 v72, v72
	v_exp_f32_e32 v73, v73
	v_add_u32_e32 v94, s35, v213
	ds_read_b128 v[174:177], v94
	ds_read_b128 v[170:173], v94 offset:512
	s_waitcnt lgkmcnt(12)
	v_mfma_f32_32x32x16_bf16 v[2:17], v[138:141], v[102:105], v[2:17]
	v_exp_f32_e32 v74, v74
	v_exp_f32_e32 v75, v75
	v_exp_f32_e32 v76, v76
	v_exp_f32_e32 v77, v77
	ds_read_b128 v[166:169], v94 offset:2048
	ds_read_b128 v[162:165], v94 offset:2560
	s_waitcnt lgkmcnt(12)
	v_mfma_f32_32x32x16_bf16 v[18:33], v[138:141], v[106:109], v[18:33]
	v_exp_f32_e32 v78, v78
	v_exp_f32_e32 v79, v79
	v_exp_f32_e32 v80, v80
	v_exp_f32_e32 v81, v81
	ds_read_b128 v[158:161], v94 offset:4096
	ds_read_b128 v[154:157], v94 offset:4608
	s_waitcnt lgkmcnt(12)
	v_mfma_f32_32x32x16_bf16 v[2:17], v[130:133], v[110:113], v[2:17]
	v_exp_f32_e32 v50, v50
	v_exp_f32_e32 v51, v51
	v_exp_f32_e32 v52, v52
	v_exp_f32_e32 v53, v53
	ds_read_b128 v[150:153], v94 offset:6144
	ds_read_b128 v[146:149], v94 offset:6656
	s_waitcnt lgkmcnt(12)
	v_mfma_f32_32x32x16_bf16 v[18:33], v[130:133], v[82:85], v[18:33]
	v_exp_f32_e32 v54, v54
	v_exp_f32_e32 v55, v55
	v_exp_f32_e32 v56, v56
	v_exp_f32_e32 v57, v57
	s_waitcnt lgkmcnt(10)
	v_mfma_f32_32x32x16_bf16 v[2:17], v[122:125], v[86:89], v[2:17]
	v_exp_f32_e32 v58, v58
	v_exp_f32_e32 v59, v59
	v_exp_f32_e32 v60, v60
	v_exp_f32_e32 v61, v61
	s_waitcnt lgkmcnt(8)
	v_mfma_f32_32x32x16_bf16 v[18:33], v[122:125], v[90:93], v[18:33]
	v_exp_f32_e32 v62, v62
	v_exp_f32_e32 v63, v63
	v_exp_f32_e32 v64, v64
	v_exp_f32_e32 v65, v65
	s_add_i32 s0, s35, 0x2000
	s_waitcnt vmcnt(2) lgkmcnt(0)
	s_barrier
	s_cmpk_lg_i32 s35, 0x4000
	v_add_f32_e32 v82, v201, v182
	s_cselect_b32 s48, s0, 0
	s_add_i32 s47, s47, 2
	v_add_f32_e32 v201, v82, v183
	v_lshl_add_u64 v[178:179], v[178:179], 0, s[28:29]
	v_lshl_add_u64 v[180:181], v[180:181], 0, s[28:29]
	s_cmpk_gt_u32 s47, 0x78
	s_mov_b32 s1, s40
	s_cbranch_scc0 .LBB0_212
; #define WAIT_BAR(N) asm volatile("s_waitcnt vmcnt(" #N ") lgkmcnt(0)\n\ts_barrier":::"memory")
;   #define RESC() do{ if(resc){ asm volatile("s_waitcnt lgkmcnt(0)":::"memory"); \
;       _Pragma("unroll") for(int d_=0;d_<2;++d_) _Pragma("unroll") for(int r=0;r<16;++r)o[d_][r]*=wsf[crow(r,hi)]; } }while(0)
;   #define ROT() do{sl_prev=sl_cur;sl_cur=sl_next;sl_next=(sl_next==(NSLOT-1)*SLOTB)?0:sl_next+SLOTB;}while(0)
;   #define ENDW(tt) do{ if((tt)+3<NT){WAIT_BAR(2);} else if((tt)+2<NT){WAIT_BAR(1);} else {WAIT_BAR(0);} }while(0)
; template<int THRL> __device__ __forceinline__ void attn_unit(int S,int b,int h,int qb,const bf16*Q,const bf16*__restrict__ K,const bf16*__restrict__ V,bf16*O,char*shm,const float mref){
;     ...
;   int t=1;
;     ...
;   for(;t+5<NT;t+=2){
;     STEP(pB0,pB1,pA0,pA1,t,true,true,true);     WAIT_BAR(2); RESC(); ROT();
;     STEP(pA0,pA1,pB0,pB1,t+1,true,true,true);   WAIT_BAR(2); RESC(); ROT();
;   }
;     ...
;   for(;t+1<NT;t+=2){
;     STEP(pB0,pB1,pA0,pA1,t,(t+3<NT),(t+1<NT),(t+1<NT));       ENDW(t);   RESC(); ROT();
;     STEP(pA0,pA1,pB0,pB1,t+1,(t+4<NT),(t+2<NT),(t+2<NT));     ENDW(t+1); RESC(); ROT();
	s_cmpk_lt_u32 s47, 0x7d
	s_cbranch_scc0 .LBB0_259
	v_add_u32_e32 v182, s40, v212
	ds_read_b64_tr_b16 v[178:179], v182 offset:24576
	ds_read_b64_tr_b16 v[180:181], v182 offset:25088
	v_add_f32_e32 v82, v66, v67
	s_waitcnt lgkmcnt(9)
	v_mfma_f32_32x32x16_bf16 v[98:113], v[174:177], v[134:137], v[34:49]
	v_add_f32_e32 v82, v68, v82
	v_add_f32_e32 v82, v69, v82
	v_add_f32_e32 v82, v70, v82
	v_add_f32_e32 v122, v71, v82
	v_cvt_pk_bf16_f32 v142, v66, v67
	v_cvt_pk_bf16_f32 v143, v68, v69
	ds_read_b64_tr_b16 v[174:175], v182 offset:28672
	ds_read_b64_tr_b16 v[176:177], v182 offset:29184
	s_waitcnt lgkmcnt(10)
	v_mfma_f32_32x32x16_bf16 v[82:97], v[170:173], v[134:137], v[34:49]
	v_add_f32_e32 v66, v72, v122
	v_add_f32_e32 v66, v73, v66
	v_add_f32_e32 v66, v74, v66
	v_add_f32_e32 v66, v75, v66
	v_cvt_pk_bf16_f32 v144, v70, v71
	v_cvt_pk_bf16_f32 v145, v72, v73
	ds_read_b64_tr_b16 v[170:171], v182 offset:25600
	ds_read_b64_tr_b16 v[172:173], v182 offset:26112
	s_waitcnt lgkmcnt(11)
	v_mfma_f32_32x32x16_bf16 v[98:113], v[166:169], v[126:129], v[98:113]
	v_add_f32_e32 v66, v76, v66
	v_add_f32_e32 v66, v77, v66
	v_add_f32_e32 v66, v78, v66
	v_add_f32_e32 v66, v79, v66
	v_cvt_pk_bf16_f32 v138, v74, v75
	v_cvt_pk_bf16_f32 v139, v76, v77
	ds_read_b64_tr_b16 v[74:75], v182 offset:29696
	ds_read_b64_tr_b16 v[76:77], v182 offset:30208
	s_waitcnt lgkmcnt(12)
	v_mfma_f32_32x32x16_bf16 v[82:97], v[162:165], v[126:129], v[82:97]
	v_add_f32_e32 v66, v80, v66
	v_add_f32_e32 v66, v81, v66
	v_add_f32_e32 v66, v50, v66
	v_add_f32_e32 v66, v51, v66
	v_cvt_pk_bf16_f32 v140, v78, v79
	v_cvt_pk_bf16_f32 v141, v80, v81
	ds_read_b64_tr_b16 v[70:71], v182 offset:26624
	ds_read_b64_tr_b16 v[72:73], v182 offset:27136
	s_waitcnt lgkmcnt(13)
	v_mfma_f32_32x32x16_bf16 v[98:113], v[158:161], v[118:121], v[98:113]
	v_add_f32_e32 v66, v52, v66
	v_add_f32_e32 v66, v53, v66
	v_add_f32_e32 v66, v54, v66
	v_add_f32_e32 v78, v55, v66
	v_cvt_pk_bf16_f32 v130, v50, v51
	v_cvt_pk_bf16_f32 v131, v52, v53
	ds_read_b64_tr_b16 v[66:67], v182 offset:30720
	ds_read_b64_tr_b16 v[68:69], v182 offset:31232
	s_waitcnt lgkmcnt(14)
	v_mfma_f32_32x32x16_bf16 v[82:97], v[154:157], v[118:121], v[82:97]
	v_add_f32_e32 v50, v56, v78
	v_add_f32_e32 v50, v57, v50
	v_add_f32_e32 v50, v58, v50
	v_add_f32_e32 v50, v59, v50
	v_cvt_pk_bf16_f32 v132, v54, v55
	v_cvt_pk_bf16_f32 v133, v56, v57
	ds_read_b64_tr_b16 v[54:55], v182 offset:27648
	ds_read_b64_tr_b16 v[56:57], v182 offset:28160
	s_waitcnt lgkmcnt(14)
	v_mfma_f32_32x32x16_bf16 v[98:113], v[150:153], v[114:117], v[98:113]
	v_add_f32_e32 v50, v60, v50
	v_add_f32_e32 v50, v61, v50
	v_add_f32_e32 v50, v62, v50
	v_add_f32_e32 v78, v63, v50
	v_cvt_pk_bf16_f32 v122, v58, v59
	v_cvt_pk_bf16_f32 v123, v60, v61
	ds_read_b64_tr_b16 v[50:51], v182 offset:31744
	ds_read_b64_tr_b16 v[52:53], v182 offset:32256
	v_mfma_f32_32x32x16_bf16 v[82:97], v[146:149], v[114:117], v[82:97]
	v_add_f32_e32 v58, v64, v78
	v_add_f32_e32 v58, v65, v58
	v_add_f32_e32 v214, 0, v58
	v_cvt_pk_bf16_f32 v124, v62, v63
	v_cvt_pk_bf16_f32 v125, v64, v65
	s_add_i32 s49, s47, 5
	s_cmpk_gt_u32 s47, 0x7a
	s_cselect_b64 s[40:41], -1, 0
	s_and_b64 vcc, exec, s[40:41]
	s_cbranch_vccnz .LBB0_216
	s_lshl_b32 s24, s49, 15
	v_lshl_add_u64 v[58:59], v[192:193], 0, s[24:25]
	s_add_i32 s0, s35, s44
	s_mov_b32 s1, m0
	s_mov_b32 m0, s0
	s_nop 0
	global_load_lds_dwordx4 v[58:59], off
	s_mov_b32 m0, s1
.LBB0_216:
	s_lshl_b32 s0, s47, 15
	s_add_i32 s24, s0, 0x18000
	v_lshl_add_u64 v[58:59], v[190:191], 0, s[24:25]
	s_add_i32 s0, s48, s34
	s_mov_b32 s1, m0
	s_mov_b32 m0, s0
	s_nop 0
	global_load_lds_dwordx4 v[58:59], off
	s_mov_b32 m0, s1
	s_waitcnt lgkmcnt(14)
	v_mfma_f32_32x32x16_bf16 v[2:17], v[142:145], v[178:181], v[2:17]
	v_exp_f32_e32 v98, v98
	v_exp_f32_e32 v99, v99
	v_exp_f32_e32 v100, v100
	v_exp_f32_e32 v101, v101
	s_waitcnt lgkmcnt(12)
	v_mfma_f32_32x32x16_bf16 v[18:33], v[142:145], v[174:177], v[18:33]
	v_exp_f32_e32 v102, v102
	v_exp_f32_e32 v103, v103
	v_exp_f32_e32 v104, v104
	v_exp_f32_e32 v105, v105
	v_add_u32_e32 v58, s48, v213
	ds_read_b128 v[174:177], v58
	ds_read_b128 v[166:169], v58 offset:512
	s_waitcnt lgkmcnt(12)
	v_mfma_f32_32x32x16_bf16 v[2:17], v[138:141], v[170:173], v[2:17]
	v_exp_f32_e32 v106, v106
	v_exp_f32_e32 v107, v107
	v_exp_f32_e32 v108, v108
	v_exp_f32_e32 v109, v109
	ds_read_b128 v[170:173], v58 offset:2048
	ds_read_b128 v[158:161], v58 offset:2560
	s_waitcnt lgkmcnt(12)
	v_mfma_f32_32x32x16_bf16 v[18:33], v[138:141], v[74:77], v[18:33]
	v_exp_f32_e32 v110, v110
	v_exp_f32_e32 v111, v111
	v_exp_f32_e32 v112, v112
	v_exp_f32_e32 v113, v113
	ds_read_b128 v[162:165], v58 offset:4096
	ds_read_b128 v[150:153], v58 offset:4608
	s_waitcnt lgkmcnt(12)
	v_mfma_f32_32x32x16_bf16 v[2:17], v[130:133], v[70:73], v[2:17]
	v_exp_f32_e32 v82, v82
	v_exp_f32_e32 v83, v83
	v_exp_f32_e32 v84, v84
	v_exp_f32_e32 v85, v85
	ds_read_b128 v[154:157], v58 offset:6144
	ds_read_b128 v[146:149], v58 offset:6656
	s_waitcnt lgkmcnt(12)
	v_mfma_f32_32x32x16_bf16 v[18:33], v[130:133], v[66:69], v[18:33]
	v_exp_f32_e32 v86, v86
	v_exp_f32_e32 v87, v87
	v_exp_f32_e32 v88, v88
	v_exp_f32_e32 v89, v89
	s_waitcnt lgkmcnt(10)
	v_mfma_f32_32x32x16_bf16 v[2:17], v[122:125], v[54:57], v[2:17]
	v_exp_f32_e32 v90, v90
	v_exp_f32_e32 v91, v91
	v_exp_f32_e32 v92, v92
	v_exp_f32_e32 v93, v93
	s_waitcnt lgkmcnt(8)
	v_mfma_f32_32x32x16_bf16 v[18:33], v[122:125], v[50:53], v[18:33]
	v_exp_f32_e32 v94, v94
	v_exp_f32_e32 v95, v95
	v_exp_f32_e32 v96, v96
	v_exp_f32_e32 v97, v97
	s_mov_b64 s[0:1], -1
	s_and_b64 vcc, exec, s[40:41]
	s_cbranch_vccz .LBB0_222
	s_cmpk_lg_i32 s47, 0x7b
	s_cbranch_scc0 .LBB0_219
	s_waitcnt vmcnt(0) lgkmcnt(0)
	s_barrier
	s_mov_b64 s[0:1], 0

; #define WAIT_BAR(N) asm volatile("s_waitcnt vmcnt(" #N ") lgkmcnt(0)\n\ts_barrier":::"memory")
;   #define RESC() do{ if(resc){ asm volatile("s_waitcnt lgkmcnt(0)":::"memory"); \
;       _Pragma("unroll") for(int d_=0;d_<2;++d_) _Pragma("unroll") for(int r=0;r<16;++r)o[d_][r]*=wsf[crow(r,hi)]; } }while(0)
;   #define ROT() do{sl_prev=sl_cur;sl_cur=sl_next;sl_next=(sl_next==(NSLOT-1)*SLOTB)?0:sl_next+SLOTB;}while(0)
;   #define ENDW(tt) do{ if((tt)+3<NT){WAIT_BAR(2);} else if((tt)+2<NT){WAIT_BAR(1);} else {WAIT_BAR(0);} }while(0)
; template<int THRL> __device__ __forceinline__ void attn_unit(int S,int b,int h,int qb,const bf16*Q,const bf16*__restrict__ K,const bf16*__restrict__ V,bf16*O,char*shm,const float mref){
;     ...
;   int t=1;
;     ...
;   for(;t+5<NT;t+=2){
;     STEP(pB0,pB1,pA0,pA1,t,true,true,true);     WAIT_BAR(2); RESC(); ROT();
;     STEP(pA0,pA1,pB0,pB1,t+1,true,true,true);   WAIT_BAR(2); RESC(); ROT();
;   }
;     ...
;   for(;t+1<NT;t+=2){
;     STEP(pB0,pB1,pA0,pA1,t,(t+3<NT),(t+1<NT),(t+1<NT));       ENDW(t);   RESC(); ROT();
;     STEP(pA0,pA1,pB0,pB1,t+1,(t+4<NT),(t+2<NT),(t+2<NT));     ENDW(t+1); RESC(); ROT();
.LBB0_224:
	v_add_u32_e32 v204, s35, v212
	ds_read_b64_tr_b16 v[186:187], v204 offset:24576
	ds_read_b64_tr_b16 v[188:189], v204 offset:25088
	v_add_f32_e32 v50, v98, v99
	s_waitcnt lgkmcnt(9)
	v_mfma_f32_32x32x16_bf16 v[66:81], v[174:177], v[134:137], v[34:49]
	v_add_f32_e32 v50, v100, v50
	v_add_f32_e32 v50, v101, v50
	v_add_f32_e32 v50, v102, v50
	v_add_f32_e32 v122, v103, v50
	v_cvt_pk_bf16_f32 v142, v98, v99
	v_cvt_pk_bf16_f32 v143, v100, v101
	ds_read_b64_tr_b16 v[182:183], v204 offset:28672
	ds_read_b64_tr_b16 v[184:185], v204 offset:29184
	s_waitcnt lgkmcnt(10)
	v_mfma_f32_32x32x16_bf16 v[50:65], v[166:169], v[134:137], v[34:49]
	v_add_f32_e32 v98, v104, v122
	v_add_f32_e32 v98, v105, v98
	v_add_f32_e32 v98, v106, v98
	v_add_f32_e32 v98, v107, v98
	v_cvt_pk_bf16_f32 v144, v102, v103
	v_cvt_pk_bf16_f32 v145, v104, v105
	ds_read_b64_tr_b16 v[178:179], v204 offset:25600
	ds_read_b64_tr_b16 v[180:181], v204 offset:26112
	s_waitcnt lgkmcnt(11)
	v_mfma_f32_32x32x16_bf16 v[66:81], v[170:173], v[126:129], v[66:81]
	v_add_f32_e32 v98, v108, v98
	v_add_f32_e32 v98, v109, v98
	v_add_f32_e32 v98, v110, v98
	v_add_f32_e32 v98, v111, v98
	v_cvt_pk_bf16_f32 v138, v106, v107
	v_cvt_pk_bf16_f32 v139, v108, v109
	ds_read_b64_tr_b16 v[106:107], v204 offset:29696
	ds_read_b64_tr_b16 v[108:109], v204 offset:30208
	s_waitcnt lgkmcnt(12)
	v_mfma_f32_32x32x16_bf16 v[50:65], v[158:161], v[126:129], v[50:65]
	v_add_f32_e32 v98, v112, v98
	v_add_f32_e32 v98, v113, v98
	v_add_f32_e32 v98, v82, v98
	v_add_f32_e32 v98, v83, v98
	v_cvt_pk_bf16_f32 v140, v110, v111
	v_cvt_pk_bf16_f32 v141, v112, v113
	ds_read_b64_tr_b16 v[102:103], v204 offset:26624
	ds_read_b64_tr_b16 v[104:105], v204 offset:27136
	s_waitcnt lgkmcnt(13)
	v_mfma_f32_32x32x16_bf16 v[66:81], v[162:165], v[118:121], v[66:81]
	v_add_f32_e32 v98, v84, v98
	v_add_f32_e32 v98, v85, v98
	v_add_f32_e32 v98, v86, v98
	v_add_f32_e32 v110, v87, v98
	v_cvt_pk_bf16_f32 v130, v82, v83
	v_cvt_pk_bf16_f32 v131, v84, v85
	ds_read_b64_tr_b16 v[98:99], v204 offset:30720
	ds_read_b64_tr_b16 v[100:101], v204 offset:31232
	s_waitcnt lgkmcnt(14)
	v_mfma_f32_32x32x16_bf16 v[50:65], v[150:153], v[118:121], v[50:65]
	v_add_f32_e32 v82, v88, v110
	v_add_f32_e32 v82, v89, v82
	v_add_f32_e32 v82, v90, v82
	v_add_f32_e32 v82, v91, v82
	v_cvt_pk_bf16_f32 v132, v86, v87
	v_cvt_pk_bf16_f32 v133, v88, v89
	ds_read_b64_tr_b16 v[86:87], v204 offset:27648
	ds_read_b64_tr_b16 v[88:89], v204 offset:28160
	s_waitcnt lgkmcnt(14)
	v_mfma_f32_32x32x16_bf16 v[66:81], v[154:157], v[114:117], v[66:81]
	v_add_f32_e32 v82, v92, v82
	v_add_f32_e32 v82, v93, v82
	v_add_f32_e32 v82, v94, v82
	v_add_f32_e32 v110, v95, v82
	v_cvt_pk_bf16_f32 v122, v90, v91
	v_cvt_pk_bf16_f32 v123, v92, v93
	ds_read_b64_tr_b16 v[82:83], v204 offset:31744
	ds_read_b64_tr_b16 v[84:85], v204 offset:32256
	v_mfma_f32_32x32x16_bf16 v[50:65], v[146:149], v[114:117], v[50:65]
	v_add_f32_e32 v90, v96, v110
	v_add_f32_e32 v90, v97, v90
	v_add_f32_e32 v215, 0, v90
	v_cvt_pk_bf16_f32 v124, v94, v95
	v_cvt_pk_bf16_f32 v125, v96, v97
	s_cmpk_eq_i32 s47, 0x79
	s_cselect_b64 s[36:37], -1, 0
	s_cmpk_lg_i32 s47, 0x79
	s_cselect_b64 s[42:43], -1, 0
	s_and_b64 vcc, exec, s[42:43]
	s_cbranch_vccnz .LBB0_226
	s_mov_b64 s[0:1], 0x3f8000
	v_lshl_add_u64 v[90:91], v[192:193], 0, s[0:1]
	s_add_i32 s0, s48, s44
	s_mov_b32 s1, m0
	s_mov_b32 m0, s0
	s_nop 0
	global_load_lds_dwordx4 v[90:91], off
	s_mov_b32 m0, s1

; #define WAIT_BAR(N) asm volatile("s_waitcnt vmcnt(" #N ") lgkmcnt(0)\n\ts_barrier":::"memory")
;   #define RESC() do{ if(resc){ asm volatile("s_waitcnt lgkmcnt(0)":::"memory"); \
;       _Pragma("unroll") for(int d_=0;d_<2;++d_) _Pragma("unroll") for(int r=0;r<16;++r)o[d_][r]*=wsf[crow(r,hi)]; } }while(0)
;   #define ROT() do{sl_prev=sl_cur;sl_cur=sl_next;sl_next=(sl_next==(NSLOT-1)*SLOTB)?0:sl_next+SLOTB;}while(0)
;   #define ENDW(tt) do{ if((tt)+3<NT){WAIT_BAR(2);} else if((tt)+2<NT){WAIT_BAR(1);} else {WAIT_BAR(0);} }while(0)
; template<int THRL> __device__ __forceinline__ void attn_unit(int S,int b,int h,int qb,const bf16*Q,const bf16*__restrict__ K,const bf16*__restrict__ V,bf16*O,char*shm,const float mref){
;     ...
;   int t=1;
;     ...
;   for(;t+5<NT;t+=2){
;     STEP(pB0,pB1,pA0,pA1,t,true,true,true);     WAIT_BAR(2); RESC(); ROT();
;     STEP(pA0,pA1,pB0,pB1,t+1,true,true,true);   WAIT_BAR(2); RESC(); ROT();
;   }
;     ...
;   for(;t+1<NT;t+=2){
;     STEP(pB0,pB1,pA0,pA1,t,(t+3<NT),(t+1<NT),(t+1<NT));       ENDW(t);   RESC(); ROT();
;     STEP(pA0,pA1,pB0,pB1,t+1,(t+4<NT),(t+2<NT),(t+2<NT));     ENDW(t+1); RESC(); ROT();
.LBB0_228:
	s_waitcnt lgkmcnt(14)
	v_mfma_f32_32x32x16_bf16 v[2:17], v[142:145], v[186:189], v[2:17]
	v_exp_f32_e32 v66, v66
	v_exp_f32_e32 v67, v67
	v_exp_f32_e32 v68, v68
	v_exp_f32_e32 v69, v69
	s_waitcnt lgkmcnt(12)
	v_mfma_f32_32x32x16_bf16 v[18:33], v[142:145], v[182:185], v[18:33]
	v_exp_f32_e32 v70, v70
	v_exp_f32_e32 v71, v71
	v_exp_f32_e32 v72, v72
	v_exp_f32_e32 v73, v73
	v_cndmask_b32_e64 v90, 0, 1, s[44:45]
	v_cmp_ne_u32_e64 s[0:1], 1, v90
	s_andn2_b64 vcc, exec, s[44:45]
	v_add_u32_e32 v90, s50, v213
	s_cbranch_vccnz .LBB0_230
	ds_read_b128 v[174:177], v90
	ds_read_b128 v[166:169], v90 offset:512
.LBB0_230:
	s_waitcnt lgkmcnt(10)
	v_mfma_f32_32x32x16_bf16 v[2:17], v[138:141], v[178:181], v[2:17]
	v_exp_f32_e32 v74, v74
	v_exp_f32_e32 v75, v75
	v_exp_f32_e32 v76, v76
	v_exp_f32_e32 v77, v77
	s_and_b64 vcc, exec, s[0:1]
	s_cbranch_vccnz .LBB0_232
	ds_read_b128 v[170:173], v90 offset:2048
	ds_read_b128 v[158:161], v90 offset:2560
.LBB0_232:
	s_waitcnt lgkmcnt(8)
	v_mfma_f32_32x32x16_bf16 v[18:33], v[138:141], v[106:109], v[18:33]
	v_exp_f32_e32 v78, v78
	v_exp_f32_e32 v79, v79
	v_exp_f32_e32 v80, v80
	v_exp_f32_e32 v81, v81
	s_and_b64 vcc, exec, s[0:1]
	s_cbranch_vccnz .LBB0_234
	ds_read_b128 v[162:165], v90 offset:4096
	ds_read_b128 v[150:153], v90 offset:4608
.LBB0_234:
	s_waitcnt lgkmcnt(6)
	v_mfma_f32_32x32x16_bf16 v[2:17], v[130:133], v[102:105], v[2:17]
	v_exp_f32_e32 v50, v50
	v_exp_f32_e32 v51, v51
	v_exp_f32_e32 v52, v52
	v_exp_f32_e32 v53, v53
	s_and_b64 vcc, exec, s[0:1]
	s_cbranch_vccnz .LBB0_236
	ds_read_b128 v[154:157], v90 offset:6144
	ds_read_b128 v[146:149], v90 offset:6656
.LBB0_236:
	s_waitcnt lgkmcnt(4)
	v_mfma_f32_32x32x16_bf16 v[18:33], v[130:133], v[98:101], v[18:33]
	v_exp_f32_e32 v54, v54
	v_exp_f32_e32 v55, v55
	v_exp_f32_e32 v56, v56
	v_exp_f32_e32 v57, v57
	s_waitcnt lgkmcnt(2)
	v_mfma_f32_32x32x16_bf16 v[2:17], v[122:125], v[86:89], v[2:17]
	v_exp_f32_e32 v58, v58
	v_exp_f32_e32 v59, v59
	v_exp_f32_e32 v60, v60
	v_exp_f32_e32 v61, v61
	s_waitcnt lgkmcnt(0)
	v_mfma_f32_32x32x16_bf16 v[18:33], v[122:125], v[82:85], v[18:33]
	v_exp_f32_e32 v62, v62
	v_exp_f32_e32 v63, v63
	v_exp_f32_e32 v64, v64
	v_exp_f32_e32 v65, v65
	s_mov_b64 s[0:1], -1
	s_and_b64 vcc, exec, s[42:43]
	s_cbranch_vccz .LBB0_242
	s_and_b64 vcc, exec, s[40:41]
	s_cbranch_vccz .LBB0_239
	s_waitcnt vmcnt(0) lgkmcnt(0)
	s_barrier
	s_mov_b64 s[0:1], 0

; #define WAIT_BAR(N) asm volatile("s_waitcnt vmcnt(" #N ") lgkmcnt(0)\n\ts_barrier":::"memory")
;   #define RESC() do{ if(resc){ asm volatile("s_waitcnt lgkmcnt(0)":::"memory"); \
;       _Pragma("unroll") for(int d_=0;d_<2;++d_) _Pragma("unroll") for(int r=0;r<16;++r)o[d_][r]*=wsf[crow(r,hi)]; } }while(0)
;   #define ROT() do{sl_prev=sl_cur;sl_cur=sl_next;sl_next=(sl_next==(NSLOT-1)*SLOTB)?0:sl_next+SLOTB;}while(0)
;   #define ENDW(tt) do{ if((tt)+3<NT){WAIT_BAR(2);} else if((tt)+2<NT){WAIT_BAR(1);} else {WAIT_BAR(0);} }while(0)
; template<int THRL> __device__ __forceinline__ void attn_unit(int S,int b,int h,int qb,const bf16*Q,const bf16*__restrict__ K,const bf16*__restrict__ V,bf16*O,char*shm,const float mref){
;     ...
;   int t=1;
;     ...
;   for(;t+5<NT;t+=2){
;     STEP(pB0,pB1,pA0,pA1,t,true,true,true);     WAIT_BAR(2); RESC(); ROT();
;     STEP(pA0,pA1,pB0,pB1,t+1,true,true,true);   WAIT_BAR(2); RESC(); ROT();
;   }
;     ...
;   for(;t+1<NT;t+=2){
;     STEP(pB0,pB1,pA0,pA1,t,(t+3<NT),(t+1<NT),(t+1<NT));       ENDW(t);   RESC(); ROT();
;     STEP(pA0,pA1,pB0,pB1,t+1,(t+4<NT),(t+2<NT),(t+2<NT));     ENDW(t+1); RESC(); ROT();
.LBB0_244:
	s_add_i32 s0, s50, 0x2000
	s_cmpk_lg_i32 s50, 0x4000
	s_cselect_b32 s40, s0, 0
	v_add_u32_e32 v182, s48, v212
	ds_read_b64_tr_b16 v[178:179], v182 offset:24576
	ds_read_b64_tr_b16 v[180:181], v182 offset:25088
	v_add_f32_e32 v82, v66, v67
	v_mfma_f32_32x32x16_bf16 v[98:113], v[174:177], v[134:137], v[34:49]
	v_add_f32_e32 v82, v68, v82
	v_add_f32_e32 v82, v69, v82
	v_add_f32_e32 v82, v70, v82
	v_add_f32_e32 v122, v71, v82
	v_cvt_pk_bf16_f32 v142, v66, v67
	v_cvt_pk_bf16_f32 v143, v68, v69
	ds_read_b64_tr_b16 v[66:67], v182 offset:28672
	ds_read_b64_tr_b16 v[68:69], v182 offset:29184
	v_mfma_f32_32x32x16_bf16 v[82:97], v[166:169], v[134:137], v[34:49]
	v_add_f32_e32 v122, v72, v122
	v_add_f32_e32 v122, v73, v122
	v_add_f32_e32 v122, v74, v122
	v_add_f32_e32 v122, v75, v122
	v_cvt_pk_bf16_f32 v144, v70, v71
	v_cvt_pk_bf16_f32 v145, v72, v73
	ds_read_b64_tr_b16 v[70:71], v182 offset:25600
	ds_read_b64_tr_b16 v[72:73], v182 offset:26112
	v_mfma_f32_32x32x16_bf16 v[98:113], v[170:173], v[126:129], v[98:113]
	v_add_f32_e32 v122, v76, v122
	v_add_f32_e32 v122, v77, v122
	v_add_f32_e32 v122, v78, v122
	v_add_f32_e32 v122, v79, v122
	v_cvt_pk_bf16_f32 v138, v74, v75
	v_cvt_pk_bf16_f32 v139, v76, v77
	ds_read_b64_tr_b16 v[74:75], v182 offset:29696
	ds_read_b64_tr_b16 v[76:77], v182 offset:30208
	v_mfma_f32_32x32x16_bf16 v[82:97], v[158:161], v[126:129], v[82:97]
	v_add_f32_e32 v122, v80, v122
	v_add_f32_e32 v122, v81, v122
	v_add_f32_e32 v122, v50, v122
	v_add_f32_e32 v122, v51, v122
	v_cvt_pk_bf16_f32 v140, v78, v79
	v_cvt_pk_bf16_f32 v141, v80, v81
	ds_read_b64_tr_b16 v[78:79], v182 offset:26624
	ds_read_b64_tr_b16 v[80:81], v182 offset:27136
	v_mfma_f32_32x32x16_bf16 v[98:113], v[162:165], v[118:121], v[98:113]
	v_add_f32_e32 v122, v52, v122
	v_add_f32_e32 v122, v53, v122
	v_add_f32_e32 v122, v54, v122
	v_add_f32_e32 v122, v55, v122
	v_cvt_pk_bf16_f32 v130, v50, v51
	v_cvt_pk_bf16_f32 v131, v52, v53
	ds_read_b64_tr_b16 v[50:51], v182 offset:30720
	ds_read_b64_tr_b16 v[52:53], v182 offset:31232
	v_mfma_f32_32x32x16_bf16 v[82:97], v[150:153], v[118:121], v[82:97]
	v_add_f32_e32 v122, v56, v122
	v_add_f32_e32 v122, v57, v122
	v_add_f32_e32 v122, v58, v122
	v_add_f32_e32 v122, v59, v122
	v_cvt_pk_bf16_f32 v132, v54, v55
	v_cvt_pk_bf16_f32 v133, v56, v57
	ds_read_b64_tr_b16 v[54:55], v182 offset:27648
	ds_read_b64_tr_b16 v[56:57], v182 offset:28160
	v_mfma_f32_32x32x16_bf16 v[98:113], v[154:157], v[114:117], v[98:113]
	v_add_f32_e32 v122, v60, v122
	v_add_f32_e32 v122, v61, v122
	v_add_f32_e32 v122, v62, v122
	v_add_f32_e32 v150, v63, v122
	v_cvt_pk_bf16_f32 v122, v58, v59
	v_cvt_pk_bf16_f32 v123, v60, v61
	ds_read_b64_tr_b16 v[58:59], v182 offset:31744
	ds_read_b64_tr_b16 v[60:61], v182 offset:32256
	v_mfma_f32_32x32x16_bf16 v[82:97], v[146:149], v[114:117], v[82:97]
	v_add_f32_e32 v124, v64, v150
	v_add_f32_e32 v124, v65, v124
	v_add_f32_e32 v192, 0, v124
	v_cvt_pk_bf16_f32 v124, v62, v63
	v_cvt_pk_bf16_f32 v125, v64, v65
	s_lshl_b32 s24, s49, 15
	v_lshl_add_u64 v[62:63], v[190:191], 0, s[24:25]
	s_add_i32 s0, s40, s34
	s_mov_b32 s1, m0
	s_mov_b32 m0, s0
	s_nop 0
	global_load_lds_dwordx4 v[62:63], off
	s_mov_b32 m0, s1
	s_waitcnt lgkmcnt(14)
	v_mfma_f32_32x32x16_bf16 v[2:17], v[142:145], v[178:181], v[2:17]
	v_exp_f32_e32 v98, v98
	v_exp_f32_e32 v99, v99
	v_exp_f32_e32 v100, v100
	v_exp_f32_e32 v101, v101
	s_waitcnt lgkmcnt(12)
	v_mfma_f32_32x32x16_bf16 v[18:33], v[142:145], v[66:69], v[18:33]
	v_exp_f32_e32 v102, v102
	v_exp_f32_e32 v103, v103
	v_exp_f32_e32 v104, v104
	v_exp_f32_e32 v105, v105
	v_add_u32_e32 v62, s40, v213
	ds_read_b128 v[174:177], v62
	ds_read_b128 v[170:173], v62 offset:512
	s_waitcnt lgkmcnt(12)
	v_mfma_f32_32x32x16_bf16 v[2:17], v[138:141], v[70:73], v[2:17]
	v_exp_f32_e32 v106, v106
	v_exp_f32_e32 v107, v107
	v_exp_f32_e32 v108, v108
	v_exp_f32_e32 v109, v109
	ds_read_b128 v[166:169], v62 offset:2048
	ds_read_b128 v[162:165], v62 offset:2560
	s_waitcnt lgkmcnt(12)
	v_mfma_f32_32x32x16_bf16 v[18:33], v[138:141], v[74:77], v[18:33]
	v_exp_f32_e32 v110, v110
	v_exp_f32_e32 v111, v111
	v_exp_f32_e32 v112, v112
	v_exp_f32_e32 v113, v113
	ds_read_b128 v[158:161], v62 offset:4096
	ds_read_b128 v[154:157], v62 offset:4608
	s_waitcnt lgkmcnt(12)
	v_mfma_f32_32x32x16_bf16 v[2:17], v[130:133], v[78:81], v[2:17]
	v_exp_f32_e32 v82, v82
	v_exp_f32_e32 v83, v83
	v_exp_f32_e32 v84, v84
	v_exp_f32_e32 v85, v85
	ds_read_b128 v[150:153], v62 offset:6144
	ds_read_b128 v[146:149], v62 offset:6656
	s_waitcnt lgkmcnt(12)
	v_mfma_f32_32x32x16_bf16 v[18:33], v[130:133], v[50:53], v[18:33]
	v_exp_f32_e32 v86, v86
	v_exp_f32_e32 v87, v87
	v_exp_f32_e32 v88, v88
	v_exp_f32_e32 v89, v89
	s_waitcnt lgkmcnt(10)
	v_mfma_f32_32x32x16_bf16 v[2:17], v[122:125], v[54:57], v[2:17]
	v_exp_f32_e32 v90, v90
	v_exp_f32_e32 v91, v91
	v_exp_f32_e32 v92, v92
	v_exp_f32_e32 v93, v93
	s_waitcnt lgkmcnt(8)
	v_mfma_f32_32x32x16_bf16 v[18:33], v[122:125], v[58:61], v[18:33]
	v_exp_f32_e32 v94, v94
	v_exp_f32_e32 v95, v95
	v_exp_f32_e32 v96, v96
	v_exp_f32_e32 v97, v97
	s_cmpk_eq_i32 s35, 0x7d
	s_mov_b64 s[0:1], -1
	s_cbranch_scc1 .LBB0_246
	s_waitcnt vmcnt(0) lgkmcnt(0)
	s_barrier
	s_mov_b64 s[0:1], 0

; #define WAIT_BAR(N) asm volatile("s_waitcnt vmcnt(" #N ") lgkmcnt(0)\n\ts_barrier":::"memory")
;   #define RESC() do{ if(resc){ asm volatile("s_waitcnt lgkmcnt(0)":::"memory"); \
;       _Pragma("unroll") for(int d_=0;d_<2;++d_) _Pragma("unroll") for(int r=0;r<16;++r)o[d_][r]*=wsf[crow(r,hi)]; } }while(0)
;   #define ROT() do{sl_prev=sl_cur;sl_cur=sl_next;sl_next=(sl_next==(NSLOT-1)*SLOTB)?0:sl_next+SLOTB;}while(0)
;   #define ENDW(tt) do{ if((tt)+3<NT){WAIT_BAR(2);} else if((tt)+2<NT){WAIT_BAR(1);} else {WAIT_BAR(0);} }while(0)
; template<int THRL> __device__ __forceinline__ void attn_unit(int S,int b,int h,int qb,const bf16*Q,const bf16*__restrict__ K,const bf16*__restrict__ V,bf16*O,char*shm,const float mref){
;     ...
;   int t=1;
;     ...
;   for(;t+5<NT;t+=2){
;     STEP(pB0,pB1,pA0,pA1,t,true,true,true);     WAIT_BAR(2); RESC(); ROT();
;     STEP(pA0,pA1,pB0,pB1,t+1,true,true,true);   WAIT_BAR(2); RESC(); ROT();
;   }
;     ...
;   for(;t+1<NT;t+=2){
;     STEP(pB0,pB1,pA0,pA1,t,(t+3<NT),(t+1<NT),(t+1<NT));       ENDW(t);   RESC(); ROT();
;     STEP(pA0,pA1,pB0,pB1,t+1,(t+4<NT),(t+2<NT),(t+2<NT));     ENDW(t+1); RESC(); ROT();
.LBB0_248:
	s_add_i32 s0, s40, 0x2000
	s_cmpk_lg_i32 s40, 0x4000
	s_cselect_b32 s35, s0, 0
	v_add_u32_e32 v193, s50, v212
	ds_read_b64_tr_b16 v[186:187], v193 offset:24576
	ds_read_b64_tr_b16 v[188:189], v193 offset:25088
	v_add_f32_e32 v50, v98, v99
	s_waitcnt lgkmcnt(9)
	v_mfma_f32_32x32x16_bf16 v[66:81], v[174:177], v[134:137], v[34:49]
	v_add_f32_e32 v50, v100, v50
	v_add_f32_e32 v50, v101, v50
	v_add_f32_e32 v50, v102, v50
	v_add_f32_e32 v122, v103, v50
	v_cvt_pk_bf16_f32 v142, v98, v99
	v_cvt_pk_bf16_f32 v143, v100, v101
	ds_read_b64_tr_b16 v[182:183], v193 offset:28672
	ds_read_b64_tr_b16 v[184:185], v193 offset:29184
	s_waitcnt lgkmcnt(10)
	v_mfma_f32_32x32x16_bf16 v[50:65], v[170:173], v[134:137], v[34:49]
	v_add_f32_e32 v98, v104, v122
	v_add_f32_e32 v98, v105, v98
	v_add_f32_e32 v98, v106, v98
	v_add_f32_e32 v98, v107, v98
	v_cvt_pk_bf16_f32 v144, v102, v103
	v_cvt_pk_bf16_f32 v145, v104, v105
	ds_read_b64_tr_b16 v[178:179], v193 offset:25600
	ds_read_b64_tr_b16 v[180:181], v193 offset:26112
	s_waitcnt lgkmcnt(11)
	v_mfma_f32_32x32x16_bf16 v[66:81], v[166:169], v[126:129], v[66:81]
	v_add_f32_e32 v98, v108, v98
	v_add_f32_e32 v98, v109, v98
	v_add_f32_e32 v98, v110, v98
	v_add_f32_e32 v98, v111, v98
	v_cvt_pk_bf16_f32 v138, v106, v107
	v_cvt_pk_bf16_f32 v139, v108, v109
	ds_read_b64_tr_b16 v[106:107], v193 offset:29696
	ds_read_b64_tr_b16 v[108:109], v193 offset:30208
	s_waitcnt lgkmcnt(12)
	v_mfma_f32_32x32x16_bf16 v[50:65], v[162:165], v[126:129], v[50:65]
	v_add_f32_e32 v98, v112, v98
	v_add_f32_e32 v98, v113, v98
	v_add_f32_e32 v98, v82, v98
	v_add_f32_e32 v98, v83, v98
	v_cvt_pk_bf16_f32 v140, v110, v111
	v_cvt_pk_bf16_f32 v141, v112, v113
	ds_read_b64_tr_b16 v[102:103], v193 offset:26624
	ds_read_b64_tr_b16 v[104:105], v193 offset:27136
	s_waitcnt lgkmcnt(13)
	v_mfma_f32_32x32x16_bf16 v[66:81], v[158:161], v[118:121], v[66:81]
	v_add_f32_e32 v98, v84, v98
	v_add_f32_e32 v98, v85, v98
	v_add_f32_e32 v98, v86, v98
	v_add_f32_e32 v110, v87, v98
	v_cvt_pk_bf16_f32 v130, v82, v83
	v_cvt_pk_bf16_f32 v131, v84, v85
	ds_read_b64_tr_b16 v[98:99], v193 offset:30720
	ds_read_b64_tr_b16 v[100:101], v193 offset:31232
	s_waitcnt lgkmcnt(14)
	v_mfma_f32_32x32x16_bf16 v[50:65], v[154:157], v[118:121], v[50:65]
	v_add_f32_e32 v82, v88, v110
	v_add_f32_e32 v82, v89, v82
	v_add_f32_e32 v82, v90, v82
	v_add_f32_e32 v82, v91, v82
	v_cvt_pk_bf16_f32 v132, v86, v87
	v_cvt_pk_bf16_f32 v133, v88, v89
	ds_read_b64_tr_b16 v[86:87], v193 offset:27648
	ds_read_b64_tr_b16 v[88:89], v193 offset:28160
	s_waitcnt lgkmcnt(14)
	v_mfma_f32_32x32x16_bf16 v[66:81], v[150:153], v[114:117], v[66:81]
	v_add_f32_e32 v82, v92, v82
	v_add_f32_e32 v82, v93, v82
	v_add_f32_e32 v82, v94, v82
	v_add_f32_e32 v110, v95, v82
	v_cvt_pk_bf16_f32 v122, v90, v91
	v_cvt_pk_bf16_f32 v123, v92, v93
	ds_read_b64_tr_b16 v[82:83], v193 offset:31744
	ds_read_b64_tr_b16 v[84:85], v193 offset:32256
	v_mfma_f32_32x32x16_bf16 v[50:65], v[146:149], v[114:117], v[50:65]
	v_add_f32_e32 v90, v96, v110
	v_add_f32_e32 v90, v97, v90
	v_add_f32_e32 v90, 0, v90
	v_cvt_pk_bf16_f32 v124, v94, v95
	v_cvt_pk_bf16_f32 v125, v96, v97
	v_cndmask_b32_e64 v91, 0, 1, s[36:37]
	v_cmp_ne_u32_e64 s[0:1], 1, v91
	s_andn2_b64 vcc, exec, s[36:37]
	s_cbranch_vccnz .LBB0_250
	s_mov_b64 s[30:31], 0x3f8000
	v_lshl_add_u64 v[92:93], v[190:191], 0, s[30:31]
	s_add_i32 s23, s35, s34
	s_mov_b32 s24, m0
	s_mov_b32 m0, s23
	s_nop 0
	global_load_lds_dwordx4 v[92:93], off
	s_mov_b32 m0, s24
.LBB0_250:
	s_waitcnt lgkmcnt(14)
	v_mfma_f32_32x32x16_bf16 v[2:17], v[142:145], v[186:189], v[2:17]
	v_exp_f32_e32 v66, v66
	v_exp_f32_e32 v67, v67
	v_exp_f32_e32 v68, v68
	v_exp_f32_e32 v69, v69
	s_waitcnt lgkmcnt(12)
	v_mfma_f32_32x32x16_bf16 v[18:33], v[142:145], v[182:185], v[18:33]
	v_exp_f32_e32 v70, v70
	v_exp_f32_e32 v71, v71
	v_exp_f32_e32 v72, v72
	v_exp_f32_e32 v73, v73
	s_and_b64 vcc, exec, s[0:1]
	v_add_u32_e32 v91, s35, v213
	s_cbranch_vccnz .LBB0_252
	ds_read_b128 v[174:177], v91
	ds_read_b128 v[170:173], v91 offset:512

; #define SBAR() __builtin_amdgcn_sched_barrier(0)
; #define WAIT_BAR(N) asm volatile("s_waitcnt vmcnt(" #N ") lgkmcnt(0)\n\ts_barrier":::"memory")
;   #define RESC() do{ if(resc){ asm volatile("s_waitcnt lgkmcnt(0)":::"memory"); \
;       _Pragma("unroll") for(int d_=0;d_<2;++d_) _Pragma("unroll") for(int r=0;r<16;++r)o[d_][r]*=wsf[crow(r,hi)]; } }while(0)
;   #define ROT() do{sl_prev=sl_cur;sl_cur=sl_next;sl_next=(sl_next==(NSLOT-1)*SLOTB)?0:sl_next+SLOTB;}while(0)
;   #define PKW(P,B) cvtpk_s(P[B],P[B+1])
;   #define ENDW(tt) do{ if((tt)+3<NT){WAIT_BAR(2);} else if((tt)+2<NT){WAIT_BAR(1);} else {WAIT_BAR(0);} }while(0)
; template<int THRL> __device__ __forceinline__ void attn_unit(int S,int b,int h,int qb,const bf16*Q,const bf16*__restrict__ K,const bf16*__restrict__ V,bf16*O,char*shm,const float mref){
;     ...
;   int t=1;
;     ...
;   for(;t+5<NT;t+=2){
;     STEP(pB0,pB1,pA0,pA1,t,true,true,true);     WAIT_BAR(2); RESC(); ROT();
;     STEP(pA0,pA1,pB0,pB1,t+1,true,true,true);   WAIT_BAR(2); RESC(); ROT();
;   }
;     ...
;   for(;t+1<NT;t+=2){
;     STEP(pB0,pB1,pA0,pA1,t,(t+3<NT),(t+1<NT),(t+1<NT));       ENDW(t);   RESC(); ROT();
;     STEP(pA0,pA1,pB0,pB1,t+1,(t+4<NT),(t+2<NT),(t+2<NT));     ENDW(t+1); RESC(); ROT();
;   }
;   STEP(pB0,pB1,pA0,pA1,NT-1,false,false,false); RESC();
;   { float sacc=pB0[0]+pB0[1]; _Pragma("unroll") for(int r=2;r<16;++r)sacc+=pB0[r]; _Pragma("unroll") for(int r=0;r<16;++r)sacc+=pB1[r]; l_reg+=sacc;
;     pw0=(u32x4){PKW(pB0,0),PKW(pB0,2),PKW(pB0,4),PKW(pB0,6)};pw1=(u32x4){PKW(pB0,8),PKW(pB0,10),PKW(pB0,12),PKW(pB0,14)};pw2=(u32x4){PKW(pB1,0),PKW(pB1,2),PKW(pB1,4),PKW(pB1,6)};pw3=(u32x4){PKW(pB1,8),PKW(pB1,10),PKW(pB1,12),PKW(pB1,14)};
;     SBAR(); pv(o,vb0+sl_cur,PAF(0),PAF(1),PAF(2),PAF(3)); }
.LBB0_258:
	v_add_f32_e32 v91, v201, v214
	v_add_f32_e32 v91, v91, v215
	v_add_f32_e32 v91, v91, v192
	v_add_f32_e32 v201, v91, v90
	s_waitcnt lgkmcnt(4)
	v_mfma_f32_32x32x16_bf16 v[18:33], v[130:133], v[98:101], v[18:33]
	v_exp_f32_e32 v54, v54
	v_exp_f32_e32 v55, v55
	v_exp_f32_e32 v56, v56
	v_exp_f32_e32 v57, v57
	s_waitcnt lgkmcnt(2)
	v_mfma_f32_32x32x16_bf16 v[2:17], v[122:125], v[86:89], v[2:17]
	v_exp_f32_e32 v58, v58
	v_exp_f32_e32 v59, v59
	v_exp_f32_e32 v60, v60
	v_exp_f32_e32 v61, v61
	s_waitcnt lgkmcnt(0)
	v_mfma_f32_32x32x16_bf16 v[18:33], v[122:125], v[82:85], v[18:33]
	v_exp_f32_e32 v62, v62
	v_exp_f32_e32 v63, v63
	v_exp_f32_e32 v64, v64
	v_exp_f32_e32 v65, v65
	s_waitcnt vmcnt(0) lgkmcnt(0)
	s_barrier
.LBB0_259:
	s_and_b32 s0, s21, 0x3fffffc0
	s_cmp_lg_u32 0, -1
	s_cselect_b32 s1, 0, 0
	s_lshl_b32 s0, s0, 2
	s_addk_i32 s1, 0x6000
	s_add_i32 s21, s0, 0
	v_add3_u32 v102, v211, s1, v210
	v_add_u32_e32 v103, s40, v212
	ds_read_b64_tr_b16 v[98:99], v103 offset:24576
	ds_read_b64_tr_b16 v[100:101], v103 offset:25088
	v_add_f32_e32 v104, v66, v67
	s_waitcnt lgkmcnt(9)
	v_mfma_f32_32x32x16_bf16 v[82:97], v[174:177], v[134:137], v[34:49]
	v_add_f32_e32 v104, v68, v104
	v_add_f32_e32 v104, v69, v104
	v_add_f32_e32 v104, v70, v104
	v_add_f32_e32 v104, v71, v104
	v_cvt_pk_bf16_f32 v142, v66, v67
	v_cvt_pk_bf16_f32 v143, v68, v69
	ds_read_b64_tr_b16 v[66:67], v103 offset:28672
	ds_read_b64_tr_b16 v[68:69], v103 offset:29184
	s_waitcnt lgkmcnt(10)
	v_mfma_f32_32x32x16_bf16 v[34:49], v[170:173], v[134:137], v[34:49]
	v_add_f32_e32 v104, v72, v104
	v_add_f32_e32 v104, v73, v104
	v_add_f32_e32 v104, v74, v104
	v_add_f32_e32 v104, v75, v104
	v_cvt_pk_bf16_f32 v144, v70, v71
	v_cvt_pk_bf16_f32 v145, v72, v73
	ds_read_b64_tr_b16 v[70:71], v103 offset:25600
	ds_read_b64_tr_b16 v[72:73], v103 offset:26112
	s_waitcnt lgkmcnt(11)
	v_mfma_f32_32x32x16_bf16 v[82:97], v[166:169], v[126:129], v[82:97]
	v_add_f32_e32 v104, v76, v104
	v_add_f32_e32 v104, v77, v104
	v_add_f32_e32 v104, v78, v104
	v_add_f32_e32 v104, v79, v104
	v_cvt_pk_bf16_f32 v138, v74, v75
	v_cvt_pk_bf16_f32 v139, v76, v77
	ds_read_b64_tr_b16 v[74:75], v103 offset:29696
	ds_read_b64_tr_b16 v[76:77], v103 offset:30208
	s_waitcnt lgkmcnt(12)
	v_mfma_f32_32x32x16_bf16 v[34:49], v[162:165], v[126:129], v[34:49]
	v_add_f32_e32 v104, v80, v104
	v_add_f32_e32 v104, v81, v104
	v_add_f32_e32 v104, v50, v104
	v_add_f32_e32 v104, v51, v104
	v_cvt_pk_bf16_f32 v140, v78, v79
	v_cvt_pk_bf16_f32 v141, v80, v81
	ds_read_b64_tr_b16 v[78:79], v103 offset:26624
	ds_read_b64_tr_b16 v[80:81], v103 offset:27136
	s_waitcnt lgkmcnt(13)
	v_mfma_f32_32x32x16_bf16 v[82:97], v[158:161], v[118:121], v[82:97]
	v_add_f32_e32 v104, v52, v104
	v_add_f32_e32 v104, v53, v104
	v_add_f32_e32 v104, v54, v104
	v_add_f32_e32 v104, v55, v104
	v_cvt_pk_bf16_f32 v130, v50, v51
	v_cvt_pk_bf16_f32 v131, v52, v53
	ds_read_b64_tr_b16 v[50:51], v103 offset:30720
	ds_read_b64_tr_b16 v[52:53], v103 offset:31232
	s_waitcnt lgkmcnt(14)
	v_mfma_f32_32x32x16_bf16 v[34:49], v[154:157], v[118:121], v[34:49]
	v_add_f32_e32 v104, v56, v104
	v_add_f32_e32 v104, v57, v104
	v_add_f32_e32 v104, v58, v104
	v_add_f32_e32 v104, v59, v104
	v_cvt_pk_bf16_f32 v132, v54, v55
	v_cvt_pk_bf16_f32 v133, v56, v57
	ds_read_b64_tr_b16 v[54:55], v103 offset:27648
	ds_read_b64_tr_b16 v[56:57], v103 offset:28160
	s_waitcnt lgkmcnt(14)
	v_mfma_f32_32x32x16_bf16 v[82:97], v[150:153], v[114:117], v[82:97]
	v_add_f32_e32 v104, v60, v104
	v_add_f32_e32 v104, v61, v104
	v_add_f32_e32 v104, v62, v104
	v_add_f32_e32 v104, v63, v104
	v_cvt_pk_bf16_f32 v122, v58, v59
	v_cvt_pk_bf16_f32 v123, v60, v61
	ds_read_b64_tr_b16 v[58:59], v103 offset:31744
	ds_read_b64_tr_b16 v[60:61], v103 offset:32256
	v_mfma_f32_32x32x16_bf16 v[34:49], v[146:149], v[114:117], v[34:49]
	v_add_f32_e32 v103, v64, v104
	v_add_f32_e32 v103, v65, v103
	v_add_f32_e32 v103, 0, v103
	v_cvt_pk_bf16_f32 v124, v62, v63
	v_cvt_pk_bf16_f32 v125, v64, v65
	s_waitcnt lgkmcnt(14)
	v_mfma_f32_32x32x16_bf16 v[2:17], v[142:145], v[98:101], v[2:17]
	v_exp_f32_e32 v82, v82
	v_exp_f32_e32 v83, v83
	v_exp_f32_e32 v84, v84
	v_exp_f32_e32 v85, v85
	s_waitcnt lgkmcnt(12)
; #define SBAR() __builtin_amdgcn_sched_barrier(0)
;   #define RESC() do{ if(resc){ asm volatile("s_waitcnt lgkmcnt(0)":::"memory"); \
;       _Pragma("unroll") for(int d_=0;d_<2;++d_) _Pragma("unroll") for(int r=0;r<16;++r)o[d_][r]*=wsf[crow(r,hi)]; } }while(0)
;   #define PKW(P,B) cvtpk_s(P[B],P[B+1])
; __device__ __forceinline__ void pv(f32x16*o,int vb,bf16x8 pa0,bf16x8 pa1,bf16x8 pa2,bf16x8 pa3){
;   #pragma unroll
;   for(int d0=0;d0<2;++d0){s16x4 lo[4],hi[4];
;     #pragma unroll
;     for(int ks=0;ks<4;++ks){
;       asm volatile("ds_read_b64_tr_b16 %0,%1 offset:%c2":"=&v"(lo[ks]):"v"(vb),"i"(d0*4096+ks*1024):"memory");
;       asm volatile("ds_read_b64_tr_b16 %0,%1 offset:%c2":"=&v"(hi[ks]):"v"(vb),"i"(d0*4096+ks*1024+512):"memory");}
;     asm volatile("s_waitcnt lgkmcnt(0)":::"memory");SBAR();
;     ...
;     o[d0]=__builtin_amdgcn_mfma_f32_32x32x16_bf16(pa0,PK(0),o[d0],0,0,0);
;     o[d0]=__builtin_amdgcn_mfma_f32_32x32x16_bf16(pa1,PK(1),o[d0],0,0,0);
;     o[d0]=__builtin_amdgcn_mfma_f32_32x32x16_bf16(pa2,PK(2),o[d0],0,0,0);
;     o[d0]=__builtin_amdgcn_mfma_f32_32x32x16_bf16(pa3,PK(3),o[d0],0,0,0);
;     ...
;   }
; template<int THRL> __device__ __forceinline__ void attn_unit(int S,int b,int h,int qb,const bf16*Q,const bf16*__restrict__ K,const bf16*__restrict__ V,bf16*O,char*shm,const float mref){
;     ...
;   STEP(pB0,pB1,pA0,pA1,NT-1,false,false,false); RESC();
;   { float sacc=pB0[0]+pB0[1]; _Pragma("unroll") for(int r=2;r<16;++r)sacc+=pB0[r]; _Pragma("unroll") for(int r=0;r<16;++r)sacc+=pB1[r]; l_reg+=sacc;
;     pw0=(u32x4){PKW(pB0,0),PKW(pB0,2),PKW(pB0,4),PKW(pB0,6)};pw1=(u32x4){PKW(pB0,8),PKW(pB0,10),PKW(pB0,12),PKW(pB0,14)};pw2=(u32x4){PKW(pB1,0),PKW(pB1,2),PKW(pB1,4),PKW(pB1,6)};pw3=(u32x4){PKW(pB1,8),PKW(pB1,10),PKW(pB1,12),PKW(pB1,14)};
;     SBAR(); pv(o,vb0+sl_cur,PAF(0),PAF(1),PAF(2),PAF(3)); }
;     ...
;   {auto rr=__builtin_amdgcn_permlane32_swap(__float_as_uint(l_reg),__float_as_uint(l_reg),false,false);l_reg=__uint_as_float(rr[0])+__uint_as_float(rr[1]);}
;   if(hi==0)wsf[32+r32]=l_reg;asm volatile("s_waitcnt lgkmcnt(0)":::"memory");
	v_mfma_f32_32x32x16_bf16 v[18:33], v[142:145], v[66:69], v[18:33]
	v_exp_f32_e32 v86, v86
	v_exp_f32_e32 v87, v87
	v_exp_f32_e32 v88, v88
	v_exp_f32_e32 v89, v89
	s_waitcnt lgkmcnt(10)
	v_mfma_f32_32x32x16_bf16 v[2:17], v[138:141], v[70:73], v[2:17]
	v_exp_f32_e32 v90, v90
	v_exp_f32_e32 v91, v91
	v_exp_f32_e32 v92, v92
	v_exp_f32_e32 v93, v93
	s_waitcnt lgkmcnt(8)
	v_mfma_f32_32x32x16_bf16 v[18:33], v[138:141], v[74:77], v[18:33]
	v_exp_f32_e32 v94, v94
	v_exp_f32_e32 v95, v95
	v_exp_f32_e32 v96, v96
	v_exp_f32_e32 v97, v97
	s_waitcnt lgkmcnt(6)
	v_mfma_f32_32x32x16_bf16 v[2:17], v[130:133], v[78:81], v[2:17]
	v_exp_f32_e32 v34, v34
	v_exp_f32_e32 v35, v35
	v_exp_f32_e32 v36, v36
	v_exp_f32_e32 v37, v37
	s_waitcnt lgkmcnt(4)
	v_mfma_f32_32x32x16_bf16 v[18:33], v[130:133], v[50:53], v[18:33]
	v_exp_f32_e32 v38, v38
	v_exp_f32_e32 v39, v39
	v_exp_f32_e32 v40, v40
	v_exp_f32_e32 v41, v41
	s_waitcnt lgkmcnt(2)
	v_mfma_f32_32x32x16_bf16 v[2:17], v[122:125], v[54:57], v[2:17]
	v_exp_f32_e32 v42, v42
	v_exp_f32_e32 v43, v43
	v_exp_f32_e32 v44, v44
	v_exp_f32_e32 v45, v45
	s_waitcnt lgkmcnt(0)
	v_mfma_f32_32x32x16_bf16 v[18:33], v[122:125], v[58:61], v[18:33]
	v_exp_f32_e32 v46, v46
	v_exp_f32_e32 v47, v47
	v_exp_f32_e32 v48, v48
	v_exp_f32_e32 v49, v49
	v_add_f32_e32 v50, v82, v83
	v_add_f32_e32 v50, v84, v50
	v_add_f32_e32 v50, v85, v50
	v_add_f32_e32 v50, v86, v50
	v_add_f32_e32 v50, v87, v50
	v_add_f32_e32 v50, v88, v50
	v_add_f32_e32 v50, v89, v50
	v_add_f32_e32 v50, v90, v50
	v_add_f32_e32 v50, v91, v50
	v_add_f32_e32 v50, v92, v50
	v_add_f32_e32 v50, v93, v50
	v_add_f32_e32 v50, v94, v50
	v_add_f32_e32 v50, v95, v50
	v_add_f32_e32 v50, v96, v50
	v_add_f32_e32 v50, v97, v50
	v_add_f32_e32 v50, v50, v34
	v_add_f32_e32 v50, v35, v50
	v_add_f32_e32 v50, v36, v50
	v_add_f32_e32 v50, v37, v50
	v_add_f32_e32 v50, v38, v50
	v_add_f32_e32 v50, v39, v50
	v_add_f32_e32 v50, v40, v50
	v_add_f32_e32 v50, v41, v50
	v_add_f32_e32 v50, v42, v50
	v_add_f32_e32 v50, v43, v50
	v_add_f32_e32 v50, v44, v50
	v_add_f32_e32 v50, v45, v50
	v_add_f32_e32 v50, v46, v50
	v_add_f32_e32 v50, v47, v50
	v_add_f32_e32 v50, v48, v50
	v_add_f32_e32 v50, v49, v50
	v_add_f32_e32 v51, v201, v103
	v_add_f32_e32 v50, v51, v50
	v_cvt_pk_bf16_f32 v52, v82, v83
	v_cvt_pk_bf16_f32 v53, v84, v85
	v_cvt_pk_bf16_f32 v54, v86, v87
	v_cvt_pk_bf16_f32 v55, v88, v89
	v_cvt_pk_bf16_f32 v56, v90, v91
	v_cvt_pk_bf16_f32 v57, v92, v93
	v_cvt_pk_bf16_f32 v58, v94, v95
	v_cvt_pk_bf16_f32 v59, v96, v97
	v_cvt_pk_bf16_f32 v34, v34, v35
	v_cvt_pk_bf16_f32 v35, v36, v37
	v_cvt_pk_bf16_f32 v36, v38, v39
	v_cvt_pk_bf16_f32 v37, v40, v41
	v_cvt_pk_bf16_f32 v38, v42, v43
	v_cvt_pk_bf16_f32 v39, v44, v45
	v_cvt_pk_bf16_f32 v40, v46, v47
	v_cvt_pk_bf16_f32 v41, v48, v49
	v_add3_u32 v0, v102, v0, s35
	ds_read_b64_tr_b16 v[42:43],v0 offset:0
	ds_read_b64_tr_b16 v[44:45],v0 offset:512
	ds_read_b64_tr_b16 v[46:47],v0 offset:1024
	ds_read_b64_tr_b16 v[48:49],v0 offset:1536
	ds_read_b64_tr_b16 v[60:61],v0 offset:2048
	ds_read_b64_tr_b16 v[62:63],v0 offset:2560
	ds_read_b64_tr_b16 v[64:65],v0 offset:3072
	ds_read_b64_tr_b16 v[66:67],v0 offset:3584
	s_waitcnt lgkmcnt(0)
	s_nop 0
	v_mfma_f32_32x32x16_bf16 v[2:17], v[52:55], v[42:45], v[2:17]
	ds_read_b64_tr_b16 v[42:43],v0 offset:4096
	ds_read_b64_tr_b16 v[44:45],v0 offset:4608
	v_mfma_f32_32x32x16_bf16 v[2:17], v[56:59], v[46:49], v[2:17]
	ds_read_b64_tr_b16 v[46:47],v0 offset:5120
	ds_read_b64_tr_b16 v[48:49],v0 offset:5632
	v_mfma_f32_32x32x16_bf16 v[2:17], v[34:37], v[60:63], v[2:17]
	ds_read_b64_tr_b16 v[60:61],v0 offset:6144
	ds_read_b64_tr_b16 v[62:63],v0 offset:6656
	v_mfma_f32_32x32x16_bf16 v[2:17], v[38:41], v[64:67], v[2:17]
	ds_read_b64_tr_b16 v[64:65],v0 offset:7168
	ds_read_b64_tr_b16 v[66:67],v0 offset:7680
	s_waitcnt lgkmcnt(0)
	v_mfma_f32_32x32x16_bf16 v[18:33], v[52:55], v[42:45], v[18:33]
	v_mov_b32_e32 v0, v50
	s_nop 1
	v_permlane32_swap_b32_e32 v50, v0
	v_cmp_gt_u32_e32 vcc, 32, v197
	v_mfma_f32_32x32x16_bf16 v[18:33], v[56:59], v[46:49], v[18:33]
	v_mfma_f32_32x32x16_bf16 v[18:33], v[34:37], v[60:63], v[18:33]
	v_mfma_f32_32x32x16_bf16 v[18:33], v[38:41], v[64:67], v[18:33]
	s_and_saveexec_b64 s[0:1], vcc
	s_cbranch_execz .LBB0_210
	v_add_f32_e32 v0, v50, v0
	v_lshl_add_u32 v34, v199, 2, s21
	ds_write_b32 v34, v0 offset:49280
	s_branch .LBB0_210
